# v20 + ATTD epilogue gamma loads hoisted, hand-written GEMM epilogue fast paths for modes 0,5,3,1 (replace branchy general path)
# speedup vs baseline: 1.0208x; 1.0039x over previous
; DI void phase_attd(ArgsP AP, LAS unsigned char* lds, int rep) {
;     ...
;         if (comp == 0) { const float inv = 1.f / lsum; float ss = 0.f;
; #pragma unroll
;             for (int db = 0; db < 4; ++db)
; #pragma unroll
;                 for (int i = 0; i < 16; ++i) { const float o = O[db][i] * inv - X[(wq * 64 + db * 16 + i) * 64 + lane]; O[db][i] = o; ss += o * o; }
.LBB0_211:
	s_andn2_b64 vcc, exec, s[22:23]
	s_waitcnt lgkmcnt(0)
	s_barrier
	s_cbranch_vccnz .LBB0_157
	v_div_scale_f32 v65, s[2:3], v64, v64, 1.0
	v_rcp_f32_e32 v66, v65
	v_div_scale_f32 v67, vcc, 1.0, v64, 1.0
	v_fma_f32 v68, -v65, v66, 1.0
	v_fmac_f32_e32 v66, v68, v66
	v_mul_f32_e32 v68, v67, v66
	v_fma_f32 v69, -v65, v68, v67
	v_fmac_f32_e32 v68, v69, v66
	v_fma_f32 v65, -v65, v68, v67
	v_div_fmas_f32 v65, v65, v66, v68
	ds_read2st64_b32 v[66:67], v239 offset1:1
	ds_read2st64_b32 v[68:69], v239 offset0:2 offset1:3
	ds_read2st64_b32 v[76:77], v239 offset0:4 offset1:5
	ds_read2st64_b32 v[78:79], v239 offset0:6 offset1:7
	v_div_fixup_f32 v70, v65, v64, 1.0
	v_cmp_gt_u32_e32 vcc, s37, v168
	s_waitcnt lgkmcnt(2)
	v_pk_fma_f32 v[50:51], v[50:51], v[70:71], v[68:69] op_sel_hi:[1,0,1] neg_lo:[0,0,1] neg_hi:[0,0,1]
	v_pk_fma_f32 v[64:65], v[48:49], v[70:71], v[66:67] op_sel_hi:[1,0,1] neg_lo:[0,0,1] neg_hi:[0,0,1]
	s_waitcnt lgkmcnt(1)
	v_pk_fma_f32 v[48:49], v[52:53], v[70:71], v[76:77] op_sel_hi:[1,0,1] neg_lo:[0,0,1] neg_hi:[0,0,1]
	s_waitcnt lgkmcnt(0)
	v_pk_fma_f32 v[52:53], v[54:55], v[70:71], v[78:79] op_sel_hi:[1,0,1] neg_lo:[0,0,1] neg_hi:[0,0,1]
	ds_read2st64_b32 v[54:55], v239 offset0:8 offset1:9
	ds_read2st64_b32 v[68:69], v239 offset0:10 offset1:11
	ds_read2st64_b32 v[84:85], v239 offset0:12 offset1:13
	ds_read2st64_b32 v[86:87], v239 offset0:14 offset1:15
	v_pk_mul_f32 v[72:73], v[64:65], v[64:65]
	v_pk_mul_f32 v[74:75], v[50:51], v[50:51]
	s_waitcnt lgkmcnt(2)
	v_pk_fma_f32 v[58:59], v[58:59], v[70:71], v[68:69] op_sel_hi:[1,0,1] neg_lo:[0,0,1] neg_hi:[0,0,1]
	v_pk_fma_f32 v[66:67], v[56:57], v[70:71], v[54:55] op_sel_hi:[1,0,1] neg_lo:[0,0,1] neg_hi:[0,0,1]
	s_waitcnt lgkmcnt(1)
	v_pk_fma_f32 v[54:55], v[60:61], v[70:71], v[84:85] op_sel_hi:[1,0,1] neg_lo:[0,0,1] neg_hi:[0,0,1]
	ds_read2st64_b32 v[60:61], v239 offset0:16 offset1:17
	ds_read2st64_b32 v[68:69], v239 offset0:18 offset1:19
	ds_read2st64_b32 v[88:89], v239 offset0:20 offset1:21
	ds_read2st64_b32 v[90:91], v239 offset0:22 offset1:23
	s_waitcnt lgkmcnt(4)
	v_pk_fma_f32 v[56:57], v[62:63], v[70:71], v[86:87] op_sel_hi:[1,0,1] neg_lo:[0,0,1] neg_hi:[0,0,1]
	v_pk_mul_f32 v[76:77], v[48:49], v[48:49]
	v_pk_mul_f32 v[78:79], v[52:53], v[52:53]
	s_waitcnt lgkmcnt(3)
	v_pk_fma_f32 v[62:63], v[32:33], v[70:71], v[60:61] op_sel_hi:[1,0,1] neg_lo:[0,0,1] neg_hi:[0,0,1]
	s_waitcnt lgkmcnt(1)
	v_pk_fma_f32 v[32:33], v[36:37], v[70:71], v[88:89] op_sel_hi:[1,0,1] neg_lo:[0,0,1] neg_hi:[0,0,1]
	ds_read2st64_b32 v[36:37], v239 offset0:24 offset1:25
	v_pk_fma_f32 v[60:61], v[34:35], v[70:71], v[68:69] op_sel_hi:[1,0,1] neg_lo:[0,0,1] neg_hi:[0,0,1]
	s_waitcnt lgkmcnt(1)
	v_pk_fma_f32 v[34:35], v[38:39], v[70:71], v[90:91] op_sel_hi:[1,0,1] neg_lo:[0,0,1] neg_hi:[0,0,1]
	ds_read2st64_b32 v[38:39], v239 offset0:26 offset1:27
	ds_read2st64_b32 v[98:99], v239 offset0:28 offset1:29
	ds_read2st64_b32 v[148:149], v239 offset0:30 offset1:31
	v_pk_mul_f32 v[80:81], v[66:67], v[66:67]
	s_waitcnt lgkmcnt(3)
	v_pk_fma_f32 v[68:69], v[40:41], v[70:71], v[36:37] op_sel_hi:[1,0,1] neg_lo:[0,0,1] neg_hi:[0,0,1]
	s_waitcnt lgkmcnt(2)
	v_pk_fma_f32 v[40:41], v[42:43], v[70:71], v[38:39] op_sel_hi:[1,0,1] neg_lo:[0,0,1] neg_hi:[0,0,1]
	ds_read2st64_b32 v[42:43], v239 offset0:32 offset1:33
	s_waitcnt lgkmcnt(1)
	v_pk_fma_f32 v[38:39], v[46:47], v[70:71], v[148:149] op_sel_hi:[1,0,1] neg_lo:[0,0,1] neg_hi:[0,0,1]
	ds_read2st64_b32 v[46:47], v239 offset0:34 offset1:35
	ds_read2st64_b32 v[154:155], v239 offset0:36 offset1:37
	ds_read2st64_b32 v[156:157], v239 offset0:38 offset1:39
	v_pk_fma_f32 v[36:37], v[44:45], v[70:71], v[98:99] op_sel_hi:[1,0,1] neg_lo:[0,0,1] neg_hi:[0,0,1]
	v_pk_mul_f32 v[82:83], v[58:59], v[58:59]
	s_waitcnt lgkmcnt(3)
	v_pk_fma_f32 v[44:45], v[16:17], v[70:71], v[42:43] op_sel_hi:[1,0,1] neg_lo:[0,0,1] neg_hi:[0,0,1]
	s_waitcnt lgkmcnt(1)
	v_pk_fma_f32 v[16:17], v[20:21], v[70:71], v[154:155] op_sel_hi:[1,0,1] neg_lo:[0,0,1] neg_hi:[0,0,1]
	ds_read2st64_b32 v[20:21], v239 offset0:40 offset1:41
	v_pk_fma_f32 v[42:43], v[18:19], v[70:71], v[46:47] op_sel_hi:[1,0,1] neg_lo:[0,0,1] neg_hi:[0,0,1]
	s_waitcnt lgkmcnt(1)
	v_pk_fma_f32 v[18:19], v[22:23], v[70:71], v[156:157] op_sel_hi:[1,0,1] neg_lo:[0,0,1] neg_hi:[0,0,1]
	ds_read2st64_b32 v[22:23], v239 offset0:42 offset1:43
	ds_read2st64_b32 v[162:163], v239 offset0:44 offset1:45
	ds_read2st64_b32 v[208:209], v239 offset0:46 offset1:47
	v_pk_mul_f32 v[84:85], v[54:55], v[54:55]
	s_waitcnt lgkmcnt(3)
	v_pk_fma_f32 v[46:47], v[24:25], v[70:71], v[20:21] op_sel_hi:[1,0,1] neg_lo:[0,0,1] neg_hi:[0,0,1]
	s_waitcnt lgkmcnt(2)
	v_pk_fma_f32 v[24:25], v[26:27], v[70:71], v[22:23] op_sel_hi:[1,0,1] neg_lo:[0,0,1] neg_hi:[0,0,1]
	ds_read2st64_b32 v[26:27], v239 offset0:48 offset1:49
	s_waitcnt lgkmcnt(1)
	v_pk_fma_f32 v[22:23], v[30:31], v[70:71], v[208:209] op_sel_hi:[1,0,1] neg_lo:[0,0,1] neg_hi:[0,0,1]
	ds_read2st64_b32 v[208:209], v239 offset0:50 offset1:51
	ds_read2st64_b32 v[214:215], v239 offset0:52 offset1:53
	ds_read2st64_b32 v[216:217], v239 offset0:54 offset1:55
	v_pk_fma_f32 v[20:21], v[28:29], v[70:71], v[162:163] op_sel_hi:[1,0,1] neg_lo:[0,0,1] neg_hi:[0,0,1]
	v_pk_mul_f32 v[86:87], v[56:57], v[56:57]
	s_waitcnt lgkmcnt(3)
	v_pk_fma_f32 v[28:29], v[0:1], v[70:71], v[26:27] op_sel_hi:[1,0,1] neg_lo:[0,0,1] neg_hi:[0,0,1]
	s_waitcnt lgkmcnt(1)
	v_pk_fma_f32 v[0:1], v[4:5], v[70:71], v[214:215] op_sel_hi:[1,0,1] neg_lo:[0,0,1] neg_hi:[0,0,1]
	ds_read2st64_b32 v[4:5], v239 offset0:56 offset1:57
	v_pk_fma_f32 v[26:27], v[2:3], v[70:71], v[208:209] op_sel_hi:[1,0,1] neg_lo:[0,0,1] neg_hi:[0,0,1]
	s_waitcnt lgkmcnt(1)
; DI void phase_attd(ArgsP AP, LAS unsigned char* lds, int rep) {
;     ...
;         if (comp == 0) { const float inv = 1.f / lsum; float ss = 0.f;
; #pragma unroll
;             for (int db = 0; db < 4; ++db)
; #pragma unroll
;                 for (int i = 0; i < 16; ++i) { const float o = O[db][i] * inv - X[(wq * 64 + db * 16 + i) * 64 + lane]; O[db][i] = o; ss += o * o; }
;             ss += __shfl_xor(ss, 32);
;             const float rs = (1.f - AP->lam_init) / sqrtf(ss * (1.f / 128.f) + EPS);
;             if (myq < nvalid) { bf16* op = OA + (qrow0 + myq) * DM + hh * 128;
; #pragma unroll
;                 for (int db = 0; db < 4; ++db)
; #pragma unroll
;                     for (int g4 = 0; g4 < 4; ++g4) { const int d0 = 32 * db + 8 * g4 + 4 * h; const f32x4 gg = *(const f32x4*)(sg + d0);
	v_pk_fma_f32 v[2:3], v[6:7], v[70:71], v[216:217] op_sel_hi:[1,0,1] neg_lo:[0,0,1] neg_hi:[0,0,1]
	ds_read2st64_b32 v[6:7], v239 offset0:58 offset1:59
	ds_read2st64_b32 v[228:229], v239 offset0:60 offset1:61
	ds_read_b32 v230, v239 offset:15872
	v_pk_mul_f32 v[92:93], v[62:63], v[62:63]
	s_waitcnt lgkmcnt(3)
	v_pk_fma_f32 v[8:9], v[8:9], v[70:71], v[4:5] op_sel_hi:[1,0,1] neg_lo:[0,0,1] neg_hi:[0,0,1]
	v_add_u32_e32 v4, s81, v235
	ds_read_b32 v231, v4
	s_waitcnt lgkmcnt(3)
	v_pk_fma_f32 v[10:11], v[10:11], v[70:71], v[6:7] op_sel_hi:[1,0,1] neg_lo:[0,0,1] neg_hi:[0,0,1]
	s_waitcnt lgkmcnt(2)
	v_pk_fma_f32 v[4:5], v[12:13], v[70:71], v[228:229] op_sel_hi:[1,0,1] neg_lo:[0,0,1] neg_hi:[0,0,1]
	v_pk_mul_f32 v[94:95], v[60:61], v[60:61]
	v_pk_mul_f32 v[88:89], v[32:33], v[32:33]
	s_waitcnt lgkmcnt(0)
	v_pk_fma_f32 v[6:7], v[14:15], v[70:71], v[230:231] op_sel_hi:[1,0,1] neg_lo:[0,0,1] neg_hi:[0,0,1]
	v_add_f32_e32 v70, v72, v73
	v_add_f32_e32 v70, v70, v74
	v_add_f32_e32 v70, v70, v75
	v_add_f32_e32 v70, v70, v76
	v_add_f32_e32 v70, v70, v77
	v_add_f32_e32 v70, v70, v78
	v_add_f32_e32 v70, v70, v79
	v_add_f32_e32 v70, v70, v80
	v_add_f32_e32 v70, v70, v81
	v_add_f32_e32 v70, v70, v82
	v_add_f32_e32 v70, v70, v83
	v_add_f32_e32 v70, v70, v84
	v_add_f32_e32 v70, v70, v85
	v_add_f32_e32 v70, v70, v86
	v_add_f32_e32 v70, v70, v87
	v_add_f32_e32 v70, v70, v92
	v_add_f32_e32 v70, v70, v93
	v_add_f32_e32 v70, v70, v94
	v_add_f32_e32 v70, v70, v95
	v_add_f32_e32 v70, v70, v88
	v_pk_mul_f32 v[90:91], v[34:35], v[34:35]
	v_add_f32_e32 v70, v70, v89
	v_add_f32_e32 v70, v70, v90
	v_pk_mul_f32 v[150:151], v[68:69], v[68:69]
	v_add_f32_e32 v70, v70, v91
	v_add_f32_e32 v70, v70, v150
	v_pk_mul_f32 v[152:153], v[40:41], v[40:41]
	v_add_f32_e32 v70, v70, v151
	v_add_f32_e32 v70, v70, v152
	v_pk_mul_f32 v[98:99], v[36:37], v[36:37]
	v_add_f32_e32 v70, v70, v153
	v_add_f32_e32 v70, v70, v98
	v_pk_mul_f32 v[148:149], v[38:39], v[38:39]
	v_add_f32_e32 v70, v70, v99
	v_add_f32_e32 v70, v70, v148
	v_pk_mul_f32 v[158:159], v[44:45], v[44:45]
	v_add_f32_e32 v70, v70, v149
	v_add_f32_e32 v70, v70, v158
	v_pk_mul_f32 v[160:161], v[42:43], v[42:43]
	v_add_f32_e32 v70, v70, v159
	v_add_f32_e32 v70, v70, v160
	v_pk_mul_f32 v[154:155], v[16:17], v[16:17]
	v_add_f32_e32 v70, v70, v161
	v_add_f32_e32 v70, v70, v154
	v_pk_mul_f32 v[156:157], v[18:19], v[18:19]
	v_add_f32_e32 v70, v70, v155
	v_add_f32_e32 v70, v70, v156
	v_pk_mul_f32 v[210:211], v[46:47], v[46:47]
	v_add_f32_e32 v70, v70, v157
	v_add_f32_e32 v70, v70, v210
	v_pk_mul_f32 v[212:213], v[24:25], v[24:25]
	v_add_f32_e32 v70, v70, v211
	v_add_f32_e32 v70, v70, v212
	v_pk_mul_f32 v[162:163], v[20:21], v[20:21]
	v_add_f32_e32 v70, v70, v213
	v_add_f32_e32 v70, v70, v162
	v_pk_mul_f32 v[30:31], v[22:23], v[22:23]
	v_add_f32_e32 v70, v70, v163
	v_add_f32_e32 v30, v70, v30
	v_pk_mul_f32 v[218:219], v[28:29], v[28:29]
	v_add_f32_e32 v30, v30, v31
	v_add_f32_e32 v30, v30, v218
	v_pk_mul_f32 v[208:209], v[26:27], v[26:27]
	v_add_f32_e32 v30, v30, v219
	v_add_f32_e32 v30, v30, v208
	v_pk_mul_f32 v[214:215], v[0:1], v[0:1]
	v_add_f32_e32 v30, v30, v209
	v_add_f32_e32 v30, v30, v214
	v_pk_mul_f32 v[216:217], v[2:3], v[2:3]
	v_add_f32_e32 v30, v30, v215
	v_add_f32_e32 v30, v30, v216
	v_pk_mul_f32 v[240:241], v[8:9], v[8:9]
	v_add_f32_e32 v30, v30, v217
	v_add_f32_e32 v30, v30, v240
	v_pk_mul_f32 v[242:243], v[10:11], v[10:11]
	v_add_f32_e32 v30, v30, v241
	v_add_f32_e32 v30, v30, v242
	v_pk_mul_f32 v[12:13], v[4:5], v[4:5]
	v_add_f32_e32 v30, v30, v243
	v_add_f32_e32 v12, v30, v12
	v_pk_mul_f32 v[14:15], v[6:7], v[6:7]
	v_add_f32_e32 v12, v12, v13
	v_add_f32_e32 v12, v12, v14
	v_add_f32_e32 v12, v12, v15
	ds_bpermute_b32 v13, v71, v12
	s_and_saveexec_b64 s[2:3], vcc
	s_cbranch_execz .LBB0_156
	global_load_dwordx4 v[70:73], v[190:191], off
	global_load_dwordx4 v[100:103], v[190:191], off offset:32
	global_load_dwordx4 v[104:107], v[190:191], off offset:64
	global_load_dwordx4 v[108:111], v[190:191], off offset:96
	global_load_dwordx4 v[112:115], v[190:191], off offset:128
	global_load_dwordx4 v[116:119], v[190:191], off offset:160
	global_load_dwordx4 v[120:123], v[190:191], off offset:192
	global_load_dwordx4 v[124:127], v[190:191], off offset:224
	global_load_dwordx4 v[128:131], v[190:191], off offset:256
	global_load_dwordx4 v[132:135], v[190:191], off offset:288
	global_load_dwordx4 v[136:139], v[190:191], off offset:320
	global_load_dwordx4 v[140:143], v[190:191], off offset:352
	global_load_dwordx4 v[144:147], v[190:191], off offset:384
	global_load_dwordx4 v[148:151], v[190:191], off offset:416
	global_load_dwordx4 v[152:155], v[190:191], off offset:448
	global_load_dwordx4 v[156:159], v[190:191], off offset:480
	s_waitcnt lgkmcnt(0)
	v_add_f32_e32 v14, v12, v13
	v_fmamk_f32 v14, v14, 0x3c000000, v221
	v_mul_f32_e32 v15, 0x4f800000, v14
	v_cmp_gt_f32_e32 vcc, s13, v14
	s_load_dword s6, s[86:87], 0x130
	v_lshl_add_u64 v[12:13], s[26:27], 0, v[168:169]
	v_cndmask_b32_e32 v14, v14, v15, vcc
	v_sqrt_f32_e32 v15, v14
	v_lshlrev_b64 v[12:13], 11, v[12:13]
	s_waitcnt lgkmcnt(0)
; DI unsigned pk2(float lo, float hi) { f32x2 v = {lo, hi}; bf16x2_t b = __builtin_convertvector(v, bf16x2_t); return __builtin_bit_cast(unsigned, b); }
; DI void phase_attd(ArgsP AP, LAS unsigned char* lds, int rep) {
;     ...
;             const float rs = (1.f - AP->lam_init) / sqrtf(ss * (1.f / 128.f) + EPS);
;             if (myq < nvalid) { bf16* op = OA + (qrow0 + myq) * DM + hh * 128;
; #pragma unroll
;                 for (int db = 0; db < 4; ++db)
; #pragma unroll
;                     for (int g4 = 0; g4 < 4; ++g4) { const int d0 = 32 * db + 8 * g4 + 4 * h; const f32x4 gg = *(const f32x4*)(sg + d0);
;                         u32x2 w; w.x = pk2(O[db][4 * g4] * rs * gg[0], O[db][4 * g4 + 1] * rs * gg[1]); w.y = pk2(O[db][4 * g4 + 2] * rs * gg[2], O[db][4 * g4 + 3] * rs * gg[3]);
;                         *(u32x2*)(op + d0) = w; } }
	v_sub_f32_e64 v74, 1.0, s6
	v_lshl_add_u64 v[12:13], s[16:17], 0, v[12:13]
	v_add_u32_e32 v30, -1, v15
	v_add_u32_e32 v31, 1, v15
	v_fma_f32 v75, -v30, v15, v14
	v_fma_f32 v76, -v31, v15, v14
	v_cmp_ge_f32_e64 s[42:43], 0, v75
	v_lshlrev_b32_e32 v96, 1, v180
	v_lshl_add_u64 v[12:13], s[60:61], 1, v[12:13]
	v_cndmask_b32_e64 v15, v15, v30, s[42:43]
	v_cmp_lt_f32_e64 s[42:43], 0, v76
	s_nop 1
	v_cndmask_b32_e64 v15, v15, v31, s[42:43]
	v_mul_f32_e32 v30, 0x37800000, v15
	v_cndmask_b32_e32 v15, v15, v30, vcc
	v_cmp_class_f32_e32 vcc, v14, v222
	v_lshl_add_u64 v[30:31], v[12:13], 0, v[96:97]
	s_nop 0
	v_cndmask_b32_e32 v14, v15, v14, vcc
	v_div_scale_f32 v15, s[14:15], v14, v14, v74
	v_rcp_f32_e32 v75, v15
	v_div_scale_f32 v12, vcc, v74, v14, v74
	v_fma_f32 v13, -v15, v75, 1.0
	v_fmac_f32_e32 v75, v13, v75
	v_mul_f32_e32 v13, v12, v75
	v_fma_f32 v76, -v15, v13, v12
	v_fmac_f32_e32 v13, v76, v75
	v_fma_f32 v12, -v15, v13, v12
	v_div_fmas_f32 v12, v12, v75, v13
	v_div_fixup_f32 v74, v12, v14, v74
	v_pk_mul_f32 v[12:13], v[64:65], v[74:75] op_sel_hi:[1,0]
	v_pk_mul_f32 v[14:15], v[50:51], v[74:75] op_sel_hi:[1,0]
	v_pk_mul_f32 v[48:49], v[48:49], v[74:75] op_sel_hi:[1,0]
	v_pk_mul_f32 v[50:51], v[52:53], v[74:75] op_sel_hi:[1,0]
	v_pk_mul_f32 v[32:33], v[32:33], v[74:75] op_sel_hi:[1,0]
	v_pk_mul_f32 v[34:35], v[34:35], v[74:75] op_sel_hi:[1,0]
	v_pk_mul_f32 v[16:17], v[16:17], v[74:75] op_sel_hi:[1,0]
	v_pk_mul_f32 v[18:19], v[18:19], v[74:75] op_sel_hi:[1,0]
	v_pk_mul_f32 v[0:1], v[0:1], v[74:75] op_sel_hi:[1,0]
	v_pk_mul_f32 v[2:3], v[2:3], v[74:75] op_sel_hi:[1,0]
	v_pk_mul_f32 v[8:9], v[8:9], v[74:75] op_sel_hi:[1,0]
	v_pk_mul_f32 v[10:11], v[10:11], v[74:75] op_sel_hi:[1,0]
	v_pk_mul_f32 v[4:5], v[4:5], v[74:75] op_sel_hi:[1,0]
	v_pk_mul_f32 v[6:7], v[6:7], v[74:75] op_sel_hi:[1,0]
	s_waitcnt vmcnt(0)
	v_pk_mul_f32 v[12:13], v[12:13], v[70:71]
	v_pk_mul_f32 v[14:15], v[14:15], v[72:73]
	v_cvt_pk_bf16_f32 v12, v12, v13
	v_cvt_pk_bf16_f32 v13, v14, v15
	global_store_dwordx2 v[30:31], v[12:13], off
	v_pk_mul_f32 v[12:13], v[48:49], v[100:101]
	v_pk_mul_f32 v[14:15], v[50:51], v[102:103]
	v_cvt_pk_bf16_f32 v12, v12, v13
	v_cvt_pk_bf16_f32 v13, v14, v15
	global_store_dwordx2 v[30:31], v[12:13], off offset:16
	v_pk_mul_f32 v[48:49], v[66:67], v[74:75] op_sel_hi:[1,0]
	v_pk_mul_f32 v[50:51], v[58:59], v[74:75] op_sel_hi:[1,0]
	v_pk_mul_f32 v[12:13], v[48:49], v[104:105]
	v_pk_mul_f32 v[14:15], v[50:51], v[106:107]
	v_cvt_pk_bf16_f32 v12, v12, v13
	v_cvt_pk_bf16_f32 v13, v14, v15
	global_store_dwordx2 v[30:31], v[12:13], off offset:32
	v_pk_mul_f32 v[48:49], v[54:55], v[74:75] op_sel_hi:[1,0]
	v_pk_mul_f32 v[50:51], v[56:57], v[74:75] op_sel_hi:[1,0]
	v_pk_mul_f32 v[12:13], v[48:49], v[108:109]
	v_pk_mul_f32 v[14:15], v[50:51], v[110:111]
	v_cvt_pk_bf16_f32 v12, v12, v13
	v_cvt_pk_bf16_f32 v13, v14, v15
	global_store_dwordx2 v[30:31], v[12:13], off offset:48
	v_pk_mul_f32 v[48:49], v[62:63], v[74:75] op_sel_hi:[1,0]
	v_pk_mul_f32 v[50:51], v[60:61], v[74:75] op_sel_hi:[1,0]
	v_pk_mul_f32 v[12:13], v[48:49], v[112:113]
	v_pk_mul_f32 v[14:15], v[50:51], v[114:115]
	v_cvt_pk_bf16_f32 v12, v12, v13
	v_cvt_pk_bf16_f32 v13, v14, v15
	global_store_dwordx2 v[30:31], v[12:13], off offset:64
	v_pk_mul_f32 v[12:13], v[32:33], v[116:117]
	v_pk_mul_f32 v[14:15], v[34:35], v[118:119]
	v_cvt_pk_bf16_f32 v12, v12, v13
	v_cvt_pk_bf16_f32 v13, v14, v15
	global_store_dwordx2 v[30:31], v[12:13], off offset:80
	v_pk_mul_f32 v[32:33], v[68:69], v[74:75] op_sel_hi:[1,0]
	v_pk_mul_f32 v[34:35], v[40:41], v[74:75] op_sel_hi:[1,0]
	v_pk_mul_f32 v[12:13], v[32:33], v[120:121]
	v_pk_mul_f32 v[14:15], v[34:35], v[122:123]
	v_cvt_pk_bf16_f32 v12, v12, v13
	v_cvt_pk_bf16_f32 v13, v14, v15
	global_store_dwordx2 v[30:31], v[12:13], off offset:96
	v_pk_mul_f32 v[32:33], v[36:37], v[74:75] op_sel_hi:[1,0]
	v_pk_mul_f32 v[34:35], v[38:39], v[74:75] op_sel_hi:[1,0]
	v_pk_mul_f32 v[12:13], v[32:33], v[124:125]
	v_pk_mul_f32 v[14:15], v[34:35], v[126:127]
	v_cvt_pk_bf16_f32 v12, v12, v13
	v_cvt_pk_bf16_f32 v13, v14, v15
	global_store_dwordx2 v[30:31], v[12:13], off offset:112
	v_pk_mul_f32 v[32:33], v[44:45], v[74:75] op_sel_hi:[1,0]
	v_pk_mul_f32 v[34:35], v[42:43], v[74:75] op_sel_hi:[1,0]
	v_pk_mul_f32 v[12:13], v[32:33], v[128:129]
	v_pk_mul_f32 v[14:15], v[34:35], v[130:131]
	v_cvt_pk_bf16_f32 v12, v12, v13
	v_cvt_pk_bf16_f32 v13, v14, v15
	global_store_dwordx2 v[30:31], v[12:13], off offset:128
	v_pk_mul_f32 v[12:13], v[16:17], v[132:133]
	v_pk_mul_f32 v[14:15], v[18:19], v[134:135]
	v_cvt_pk_bf16_f32 v12, v12, v13
	v_cvt_pk_bf16_f32 v13, v14, v15
	global_store_dwordx2 v[30:31], v[12:13], off offset:144
	v_pk_mul_f32 v[16:17], v[46:47], v[74:75] op_sel_hi:[1,0]
	v_pk_mul_f32 v[18:19], v[24:25], v[74:75] op_sel_hi:[1,0]
	v_pk_mul_f32 v[12:13], v[16:17], v[136:137]
	v_pk_mul_f32 v[14:15], v[18:19], v[138:139]
	v_cvt_pk_bf16_f32 v12, v12, v13
	v_cvt_pk_bf16_f32 v13, v14, v15
	global_store_dwordx2 v[30:31], v[12:13], off offset:160
	v_pk_mul_f32 v[16:17], v[20:21], v[74:75] op_sel_hi:[1,0]
	v_pk_mul_f32 v[18:19], v[22:23], v[74:75] op_sel_hi:[1,0]
	v_pk_mul_f32 v[12:13], v[16:17], v[140:141]
	v_pk_mul_f32 v[14:15], v[18:19], v[142:143]
	v_cvt_pk_bf16_f32 v12, v12, v13
	v_cvt_pk_bf16_f32 v13, v14, v15
	global_store_dwordx2 v[30:31], v[12:13], off offset:176
	v_pk_mul_f32 v[16:17], v[28:29], v[74:75] op_sel_hi:[1,0]
	v_pk_mul_f32 v[18:19], v[26:27], v[74:75] op_sel_hi:[1,0]
	v_pk_mul_f32 v[12:13], v[16:17], v[144:145]
	v_pk_mul_f32 v[14:15], v[18:19], v[146:147]
	v_cvt_pk_bf16_f32 v12, v12, v13
	v_cvt_pk_bf16_f32 v13, v14, v15
	global_store_dwordx2 v[30:31], v[12:13], off offset:192
	v_pk_mul_f32 v[0:1], v[0:1], v[148:149]
	v_pk_mul_f32 v[2:3], v[2:3], v[150:151]
	v_cvt_pk_bf16_f32 v0, v0, v1
	v_cvt_pk_bf16_f32 v1, v2, v3
	global_store_dwordx2 v[30:31], v[0:1], off offset:208
	v_pk_mul_f32 v[0:1], v[8:9], v[152:153]
	v_pk_mul_f32 v[2:3], v[10:11], v[154:155]
	v_cvt_pk_bf16_f32 v0, v0, v1
	v_cvt_pk_bf16_f32 v1, v2, v3
	global_store_dwordx2 v[30:31], v[0:1], off offset:224
	v_pk_mul_f32 v[0:1], v[4:5], v[156:157]
	v_pk_mul_f32 v[2:3], v[6:7], v[158:159]
	v_cvt_pk_bf16_f32 v0, v0, v1
	v_cvt_pk_bf16_f32 v1, v2, v3
	global_store_dwordx2 v[30:31], v[0:1], off offset:240
	s_branch .LBB0_156

; DI float fexp2(float x) { return __builtin_amdgcn_exp2f(x); }
;     __device__ __forceinline__ void operator()(const f32x4 (&acc)[2][2][4][2], const Unit& u, int wr, int wc, int fr, int fq) const {
;     ...
;         const int colt = u.pn * BM;
; #pragma unroll
;         for (int ai = 0; ai < 2; ++ai)
; #pragma unroll
;             for (int m = 0; m < 4; ++m) {
;                 const int row = u.pm * BM + ai * HALF + wr * 64 + m * 16 + fr;
;                 int b, s; row_decode(row, b, s);
;                 const bool valid = row < RT, samp = row >= RP;
; #pragma unroll
;                 for (int bj = 0; bj < 2; ++bj) {
;                     const int col0 = colt + bj * HALF + wc * 32 + 8 * fq;
;                     f32x4 v0 = acc[ai][bj][m][0], v1 = acc[ai][bj][m][1];
;                     if (mode == 1) {
; #pragma unroll
;                         for (int e = 0; e < 4; ++e) {
;                             { const float x = v0[e]; const float t = 0.7978845608028654f * (x + 0.044715f * x * x * x); v0[e] = x * frcp(1.f + fexp2(-2.f * LOG2E * t)); }
;                             { const float x = v1[e]; const float t = 0.7978845608028654f * (x + 0.044715f * x * x * x); v1[e] = x * frcp(1.f + fexp2(-2.f * LOG2E * t)); }
;                         }
;                     } else if (mode == 2 || mode == 3) {
;                         const int region = colt >> 10;
;                         if (mode == 2 && region < 2 && (wc & 1) == 0) {
;                             f32x4 p0, p1;
; #pragma unroll
;                             for (int e = 0; e < 4; ++e) { p0[e] = __shfl_xor(v0[e], 16); p1[e] = __shfl_xor(v1[e], 16); }
;                             if (fq < 2) {
;                                 const int pos = (row < RP) ? s : 2048 + s;
;                                 const f32x4* rp = (const f32x4*)(rope + (size_t)pos * 16);
;                                 const f32x4 c0 = rp[0], c1 = rp[1], c2 = rp[2], c3 = rp[3];
;                                 const float sg = (fq == 0) ? -1.f : 1.f;
;                                 v0[0] = v0[0] * c0[0] + sg * p0[0] * c0[1]; v0[1] = v0[1] * c0[2] + sg * p0[1] * c0[3];
;                                 v0[2] = v0[2] * c1[0] + sg * p0[2] * c1[1]; v0[3] = v0[3] * c1[2] + sg * p0[3] * c1[3];
;                                 v1[0] = v1[0] * c2[0] + sg * p1[0] * c2[1]; v1[1] = v1[1] * c2[2] + sg * p1[1] * c2[3];
.LBB0_664:
	s_mov_b64 s[0:1], s[86:87]
	s_load_dwordx4 s[64:67], s[0:1], 0x100
	s_mov_b64 s[2:3], -1
	s_waitcnt lgkmcnt(0)
	s_add_u32 s30, s66, 0xaa00000
	s_addc_u32 s31, s67, 0
	s_add_u32 s6, s64, s23
	s_addc_u32 s7, s65, s75
	s_add_u32 s28, s6, 0x28330000
	s_addc_u32 s29, s7, 0
	v_readlane_b32 s6, v255, 11
	v_readlane_b32 s7, v255, 12
	s_and_b64 vcc, exec, s[6:7]
	s_cbranch_vccz .LBB0_955
	s_cmp_eq_u32 s85, 0
	s_cbranch_scc1 .Lepi_fast
	s_cmp_eq_u32 s85, 5
	s_cbranch_scc1 .Lepi_fast
	s_cmp_eq_u32 s85, 3
	s_cbranch_scc1 .Lepi_fast3
	s_cmp_eq_u32 s85, 1
	s_cbranch_scc1 .Lepi_fast1
	s_add_u32 s16, s66, 0x2000
	s_addc_u32 s17, s67, 0
	s_ashr_i32 s2, s59, 2
	s_cmp_lt_i32 s2, 2
	s_cselect_b64 s[34:35], -1, 0
	s_cmp_gt_u32 s59, 3
	s_cselect_b64 s[88:89], -1, 0
	s_cmp_eq_u32 s2, 1
	v_readlane_b32 s2, v255, 25
	v_readlane_b32 s3, v255, 26
	s_cselect_b32 s2, s3, s2
	v_readlane_b32 s3, v255, 13
	v_readlane_b32 s6, v255, 14
	s_cselect_b32 s3, s3, s6
	s_mov_b32 s6, 0x1ac00000
	s_cselect_b32 s6, s6, 0x1cd00000
	s_lshl_b32 s2, s2, 2
	s_add_u32 s86, s64, s2
	s_addc_u32 s87, s65, 0
	s_lshl_b32 s2, s3, 2
	s_add_u32 s38, s64, s2
	s_addc_u32 s39, s65, 0
	s_add_u32 s80, s66, s6
	s_addc_u32 s81, s67, 0
	s_lshl_b32 s74, s76, 8
	s_add_i32 s9, s74, s56
	v_or_b32_e32 v140, s9, v156
	s_movk_i32 s2, 0x7fff
	v_cmp_lt_i32_e64 s[52:53], s2, v140
	s_mov_b32 s2, 0x8000
	v_cmp_gt_i32_e64 s[54:55], s2, v140
	v_add_u32_e32 v130, 0xffff8000, v140
	s_mov_b32 s2, 0x8080
	v_cndmask_b32_e64 v96, 15, v249, s[54:55]
	v_bitop3_b32 v132, v96, s9, v156 bitop3:0xe0
	v_lshlrev_b32_e32 v96, 6, v132
	v_or_b32_e32 v131, 0x20000, v96
	v_cndmask_b32_e64 v96, v131, v96, s[54:55]
	v_mov_b32_e32 v131, v97
	v_lshrrev_b32_e32 v136, 4, v130
	v_cmp_gt_i32_e64 s[56:57], s2, v140
	v_lshlrev_b64 v[130:131], 12, v[130:131]
	v_mov_b32_e32 v133, v97
	s_movk_i32 s2, 0x840
	v_lshl_add_u64 v[172:173], s[38:39], 0, v[130:131]
	v_mad_u64_u32 v[130:131], s[2:3], v136, s2, v[132:133]
	v_ashrrev_i32_e32 v141, 31, v140
	v_lshlrev_b64 v[130:131], 11, v[130:131]
	v_lshlrev_b64 v[134:135], 12, v[140:141]
	v_lshl_add_u64 v[130:131], s[80:81], 0, v[130:131]
	s_mov_b64 s[2:3], 0x400000
	v_lshl_or_b32 v138, s59, 8, v192
	v_lshl_add_u64 v[174:175], s[16:17], 0, v[96:97]
	v_lshl_add_u64 v[144:145], s[86:87], 0, v[134:135]
	v_lshl_add_u64 v[142:143], v[130:131], 0, s[2:3]
	s_cmp_lt_i32 s85, 2
	s_mov_b64 s[2:3], -1
	s_cbranch_scc1 .LBB0_674
	v_mov_b64_e32 v[132:133], v[124:125]
	v_mov_b64_e32 v[136:137], v[58:59]
	s_cmp_lt_i32 s85, 4
	v_mov_b64_e32 v[130:131], v[122:123]
	v_mov_b64_e32 v[134:135], v[56:57]
	s_cbranch_scc0 .LBB0_673
	v_readlane_b32 s6, v255, 18
	s_and_b64 s[2:3], s[68:69], s[34:35]
	v_readlane_b32 s7, v255, 19
	s_and_b64 s[2:3], s[6:7], s[2:3]
	v_mov_b64_e32 v[136:137], v[58:59]
	v_mov_b64_e32 v[132:133], v[124:125]
	s_andn2_b64 vcc, exec, s[2:3]
	v_mov_b64_e32 v[134:135], v[56:57]
	v_mov_b64_e32 v[130:131], v[122:123]
	s_cbranch_vccnz .LBB0_987
	v_and_b32_e32 v130, 64, v224
	v_xor_b32_e32 v96, 16, v224
	v_add_u32_e32 v130, 64, v130
	v_cmp_lt_i32_e32 vcc, v96, v130
	v_mov_b64_e32 v[132:133], v[124:125]
	v_mov_b64_e32 v[136:137], v[58:59]
	v_cndmask_b32_e32 v96, v224, v96, vcc
	v_lshlrev_b32_e32 v96, 2, v96
	ds_bpermute_b32 v178, v96, v122
	ds_bpermute_b32 v176, v96, v56
	ds_bpermute_b32 v179, v96, v123
	ds_bpermute_b32 v177, v96, v57
	ds_bpermute_b32 v147, v96, v124
	ds_bpermute_b32 v139, v96, v58
	ds_bpermute_b32 v141, v96, v125
	ds_bpermute_b32 v96, v96, v59
	v_readlane_b32 s6, v255, 20
	v_mov_b64_e32 v[130:131], v[122:123]
	v_mov_b64_e32 v[134:135], v[56:57]
	v_readlane_b32 s7, v255, 21
	s_and_saveexec_b64 s[2:3], s[6:7]
	s_cbranch_execz .LBB0_670
	global_load_dwordx4 v[134:137], v[174:175], off offset:48
	global_load_dwordx4 v[180:183], v[174:175], off offset:32
	global_load_dwordx4 v[130:133], v[174:175], off offset:16
	global_load_dwordx4 v[184:187], v[174:175], off
	s_waitcnt lgkmcnt(0)
	v_pk_mul_f32 v[178:179], v[158:159], v[178:179]
	v_pk_mul_f32 v[176:177], v[158:159], v[176:177]
	s_waitcnt vmcnt(0)
	v_mov_b32_e32 v188, v184
	v_mov_b32_e32 v189, v186
	v_mov_b32_e32 v186, v185
	v_mul_f32_e32 v184, v124, v130
	v_mul_f32_e32 v130, v158, v147
	v_pk_mul_f32 v[178:179], v[178:179], v[186:187]
	v_mul_f32_e32 v186, v130, v131
	v_mul_f32_e32 v131, v158, v141
	v_mov_b32_e32 v130, v125
	v_pk_mul_f32 v[130:131], v[130:131], v[132:133]
	s_nop 0
	v_mov_b32_e32 v185, v130
	v_mov_b32_e32 v187, v131
	v_pk_fma_f32 v[130:131], v[122:123], v[188:189], v[178:179]
	v_mov_b32_e32 v178, v180
	v_mov_b32_e32 v179, v182
	v_mov_b32_e32 v182, v181
	v_mul_f32_e32 v180, v58, v134
	v_mul_f32_e32 v134, v158, v139
	v_pk_mul_f32 v[176:177], v[176:177], v[182:183]
	v_mul_f32_e32 v182, v134, v135
	v_mul_f32_e32 v135, v158, v96
	v_mov_b32_e32 v134, v59
	v_pk_mul_f32 v[134:135], v[134:135], v[136:137]
	v_pk_add_f32 v[132:133], v[184:185], v[186:187]
	v_mov_b32_e32 v181, v134
	v_mov_b32_e32 v183, v135
	v_pk_fma_f32 v[134:135], v[56:57], v[178:179], v[176:177]
	v_pk_add_f32 v[136:137], v[180:181], v[182:183]

;     __device__ __forceinline__ void operator()(const f32x4 (&acc)[2][2][4][2], const Unit& u, int wr, int wc, int fr, int fq) const {
;     ...
;         for (int ai = 0; ai < 2; ++ai)
; #pragma unroll
;             for (int m = 0; m < 4; ++m) {
;                 const int row = u.pm * BM + ai * HALF + wr * 64 + m * 16 + fr;
;                 int b, s; row_decode(row, b, s);
;                 const bool valid = row < RT, samp = row >= RP;
; #pragma unroll
;                 for (int bj = 0; bj < 2; ++bj) {
;                     const int col0 = colt + bj * HALF + wc * 32 + 8 * fq;
;                     f32x4 v0 = acc[ai][bj][m][0], v1 = acc[ai][bj][m][1];
;                     if (mode == 1) {
; #pragma unroll
;                         for (int e = 0; e < 4; ++e) {
;                             { const float x = v0[e]; const float t = 0.7978845608028654f * (x + 0.044715f * x * x * x); v0[e] = x * frcp(1.f + fexp2(-2.f * LOG2E * t)); }
;                             { const float x = v1[e]; const float t = 0.7978845608028654f * (x + 0.044715f * x * x * x); v1[e] = x * frcp(1.f + fexp2(-2.f * LOG2E * t)); }
;                         }
;                     } else if (mode == 2 || mode == 3) {
;                         const int region = colt >> 10;
;                         if (mode == 2 && region < 2 && (wc & 1) == 0) {
;                             f32x4 p0, p1;
; #pragma unroll
;                             for (int e = 0; e < 4; ++e) { p0[e] = __shfl_xor(v0[e], 16); p1[e] = __shfl_xor(v1[e], 16); }
;                             if (fq < 2) {
;                                 const int pos = (row < RP) ? s : 2048 + s;
;                                 const f32x4* rp = (const f32x4*)(rope + (size_t)pos * 16);
;                                 const f32x4 c0 = rp[0], c1 = rp[1], c2 = rp[2], c3 = rp[3];
;                                 const float sg = (fq == 0) ? -1.f : 1.f;
;                                 v0[0] = v0[0] * c0[0] + sg * p0[0] * c0[1]; v0[1] = v0[1] * c0[2] + sg * p0[1] * c0[3];
;                                 v0[2] = v0[2] * c1[0] + sg * p0[2] * c1[1]; v0[3] = v0[3] * c1[2] + sg * p0[3] * c1[3];
;                                 v1[0] = v1[0] * c2[0] + sg * p1[0] * c2[1]; v1[1] = v1[1] * c2[2] + sg * p1[1] * c2[3];
;                                 v1[2] = v1[2] * c3[0] + sg * p1[2] * c3[1]; v1[3] = v1[3] * c3[2] + sg * p1[3] * c3[3];
.Lepi_fast:
	s_add_u32 s2, s66, 0x6800000
	s_addc_u32 s3, s67, 0
	s_cmp_eq_u32 s85, 0
	s_cselect_b32 s2, s2, s30
	s_cselect_b32 s3, s3, s31
	s_lshl_b32 s6, s76, 8
	s_add_i32 s6, s6, s56
	v_or_b32_e32 v130, s6, v156
	v_mul_lo_u32 v130, v130, s70
	v_lshl_or_b32 v131, s59, 8, v192
	v_add_lshl_u32 v130, v130, v131, 1
	s_lshl_b32 s6, s70, 5
	s_lshl_b32 s7, s70, 8
	s_mov_b64 s[0:1], s[2:3]
	v_cvt_pk_bf16_f32 v132, v122, v123
	v_cvt_pk_bf16_f32 v133, v124, v125
	v_cvt_pk_bf16_f32 v134, v56, v57
	v_cvt_pk_bf16_f32 v135, v58, v59
	global_store_dwordx4 v130, v[132:135], s[0:1]
	v_cvt_pk_bf16_f32 v136, v126, v127
	v_cvt_pk_bf16_f32 v137, v128, v129
	v_cvt_pk_bf16_f32 v138, v60, v61
	v_cvt_pk_bf16_f32 v139, v62, v63
	global_store_dwordx4 v130, v[136:139], s[0:1] offset:256
	s_add_u32 s0, s0, s6
	s_addc_u32 s1, s1, 0
	v_cvt_pk_bf16_f32 v132, v118, v119
	v_cvt_pk_bf16_f32 v133, v120, v121
	v_cvt_pk_bf16_f32 v134, v52, v53
	v_cvt_pk_bf16_f32 v135, v54, v55
	global_store_dwordx4 v130, v[132:135], s[0:1]
	v_cvt_pk_bf16_f32 v136, v114, v115
	v_cvt_pk_bf16_f32 v137, v116, v117
	v_cvt_pk_bf16_f32 v138, v48, v49
	v_cvt_pk_bf16_f32 v139, v50, v51
	global_store_dwordx4 v130, v[136:139], s[0:1] offset:256
	s_add_u32 s0, s0, s6
	s_addc_u32 s1, s1, 0
	v_cvt_pk_bf16_f32 v132, v110, v111
	v_cvt_pk_bf16_f32 v133, v112, v113
	v_cvt_pk_bf16_f32 v134, v44, v45
	v_cvt_pk_bf16_f32 v135, v46, v47
	global_store_dwordx4 v130, v[132:135], s[0:1]
	v_cvt_pk_bf16_f32 v136, v106, v107
	v_cvt_pk_bf16_f32 v137, v108, v109
	v_cvt_pk_bf16_f32 v138, v40, v41
	v_cvt_pk_bf16_f32 v139, v42, v43
	global_store_dwordx4 v130, v[136:139], s[0:1] offset:256
	s_add_u32 s0, s0, s6
	s_addc_u32 s1, s1, 0
	v_cvt_pk_bf16_f32 v132, v98, v99
	v_cvt_pk_bf16_f32 v133, v100, v101
	v_cvt_pk_bf16_f32 v134, v32, v33
	v_cvt_pk_bf16_f32 v135, v34, v35
	global_store_dwordx4 v130, v[132:135], s[0:1]
	v_cvt_pk_bf16_f32 v136, v102, v103
	v_cvt_pk_bf16_f32 v137, v104, v105
	v_cvt_pk_bf16_f32 v138, v36, v37
	v_cvt_pk_bf16_f32 v139, v38, v39
	global_store_dwordx4 v130, v[136:139], s[0:1] offset:256
	s_add_u32 s0, s2, s7
	s_addc_u32 s1, s3, 0
	v_cvt_pk_bf16_f32 v132, v88, v89
	v_cvt_pk_bf16_f32 v133, v90, v91
	v_cvt_pk_bf16_f32 v134, v24, v25
	v_cvt_pk_bf16_f32 v135, v26, v27
	global_store_dwordx4 v130, v[132:135], s[0:1]
	v_cvt_pk_bf16_f32 v136, v92, v93
	v_cvt_pk_bf16_f32 v137, v94, v95
	v_cvt_pk_bf16_f32 v138, v28, v29
	v_cvt_pk_bf16_f32 v139, v30, v31
	global_store_dwordx4 v130, v[136:139], s[0:1] offset:256
	s_add_u32 s0, s0, s6
	s_addc_u32 s1, s1, 0
	v_cvt_pk_bf16_f32 v132, v84, v85
	v_cvt_pk_bf16_f32 v133, v86, v87
	v_cvt_pk_bf16_f32 v134, v20, v21
	v_cvt_pk_bf16_f32 v135, v22, v23
	global_store_dwordx4 v130, v[132:135], s[0:1]
	v_cvt_pk_bf16_f32 v136, v80, v81
	v_cvt_pk_bf16_f32 v137, v82, v83
	v_cvt_pk_bf16_f32 v138, v16, v17
	v_cvt_pk_bf16_f32 v139, v18, v19
	global_store_dwordx4 v130, v[136:139], s[0:1] offset:256
	s_add_u32 s0, s0, s6
	s_addc_u32 s1, s1, 0
	v_cvt_pk_bf16_f32 v132, v76, v77
	v_cvt_pk_bf16_f32 v133, v78, v79
	v_cvt_pk_bf16_f32 v134, v12, v13
	v_cvt_pk_bf16_f32 v135, v14, v15
	global_store_dwordx4 v130, v[132:135], s[0:1]
	v_cvt_pk_bf16_f32 v136, v72, v73
	v_cvt_pk_bf16_f32 v137, v74, v75
	v_cvt_pk_bf16_f32 v138, v8, v9
	v_cvt_pk_bf16_f32 v139, v10, v11
	global_store_dwordx4 v130, v[136:139], s[0:1] offset:256
	s_add_u32 s0, s0, s6
	s_addc_u32 s1, s1, 0
	v_cvt_pk_bf16_f32 v132, v64, v65
	v_cvt_pk_bf16_f32 v133, v66, v67
	v_cvt_pk_bf16_f32 v134, v0, v1
	v_cvt_pk_bf16_f32 v135, v2, v3
	global_store_dwordx4 v130, v[132:135], s[0:1]
	v_cvt_pk_bf16_f32 v136, v68, v69
	v_cvt_pk_bf16_f32 v137, v70, v71
	v_cvt_pk_bf16_f32 v138, v4, v5
	v_cvt_pk_bf16_f32 v139, v6, v7
	global_store_dwordx4 v130, v[136:139], s[0:1] offset:256
	s_branch .LBB0_954
.Lepi_fast3:
	s_lshl_b32 s6, s76, 8
	s_add_i32 s6, s6, s56
	v_or_b32_e32 v130, s6, v156
	v_lshl_or_b32 v131, s59, 8, v192
	v_mul_lo_u32 v140, v130, s70
	v_add_lshl_u32 v140, v140, v131, 1
	s_lshl_b32 s6, s70, 5
	s_lshl_b32 s7, s70, 8
	s_mov_b64 s[0:1], s[30:31]
	s_lshr_b32 s9, s59, 2
	s_cmp_eq_u32 s9, 0
	s_cbranch_scc1 .Lepi3_q
	s_add_u32 s14, s64, 0x18230000
	s_addc_u32 s15, s65, 0
	s_add_u32 s16, s64, 0x20230000
	s_addc_u32 s17, s65, 0
	s_cmp_eq_u32 s9, 1
	s_cselect_b32 s14, s14, s16
	s_cselect_b32 s15, s15, s17
	v_and_b32_e32 v131, 0x3ff, v131
	v_lshlrev_b32_e32 v141, 12, v130
	v_lshl_add_u32 v141, v131, 2, v141
	s_mov_b64 s[16:17], s[14:15]
	global_store_dwordx4 v141, v[122:125], s[16:17] nt
	global_store_dwordx4 v141, v[56:59], s[16:17] offset:16 nt
	v_cvt_pk_bf16_f32 v132, v122, v123
	v_cvt_pk_bf16_f32 v133, v124, v125
	v_cvt_pk_bf16_f32 v134, v56, v57
	v_cvt_pk_bf16_f32 v135, v58, v59
	global_store_dwordx4 v140, v[132:135], s[0:1]
	global_store_dwordx4 v141, v[126:129], s[16:17] offset:512 nt
	global_store_dwordx4 v141, v[60:63], s[16:17] offset:528 nt
	v_cvt_pk_bf16_f32 v136, v126, v127
	v_cvt_pk_bf16_f32 v137, v128, v129
	v_cvt_pk_bf16_f32 v138, v60, v61
	v_cvt_pk_bf16_f32 v139, v62, v63
	global_store_dwordx4 v140, v[136:139], s[0:1] offset:256
	s_add_u32 s0, s0, s6
	s_addc_u32 s1, s1, 0
	s_add_u32 s16, s16, 0x10000
	s_addc_u32 s17, s17, 0
	global_store_dwordx4 v141, v[118:121], s[16:17] nt
	global_store_dwordx4 v141, v[52:55], s[16:17] offset:16 nt
	v_cvt_pk_bf16_f32 v132, v118, v119
	v_cvt_pk_bf16_f32 v133, v120, v121
	v_cvt_pk_bf16_f32 v134, v52, v53
	v_cvt_pk_bf16_f32 v135, v54, v55
	global_store_dwordx4 v140, v[132:135], s[0:1]
	global_store_dwordx4 v141, v[114:117], s[16:17] offset:512 nt
	global_store_dwordx4 v141, v[48:51], s[16:17] offset:528 nt
	v_cvt_pk_bf16_f32 v136, v114, v115
	v_cvt_pk_bf16_f32 v137, v116, v117
	v_cvt_pk_bf16_f32 v138, v48, v49
; DI unsigned pk2(float lo, float hi) { f32x2 v = {lo, hi}; bf16x2_t b = __builtin_convertvector(v, bf16x2_t); return __builtin_bit_cast(unsigned, b); }
;     __device__ __forceinline__ void operator()(const f32x4 (&acc)[2][2][4][2], const Unit& u, int wr, int wc, int fr, int fq) const {
;     ...
;                         if (region == 0) { const float sc = (mode == 2) ? QSCALE_DIFF : QSCALE_SB; v0 = v0 * sc; v1 = v1 * sc; }
;                         else if (valid) {
;                             const int kc = col0 & 1023;
;                             float* dst = samp ? ((region == 1 ? oks : ovs) + (size_t)(row - RP) * DM + kc) : ((region == 1 ? okp : ovp) + (size_t)row * DM + kc);
;                             __builtin_nontemporal_store(v0, (f32x4*)dst); __builtin_nontemporal_store(v1, (f32x4*)(dst + 4));
;                             if (samp) {
;                                 bf16_t* cd = (region == 1 ? KC : VC) + ((size_t)(b - 16) * CROWS + 2048 + s) * DM + kc;
;                                 u32x4 w; w.x = pk2(v0[0], v0[1]); w.y = pk2(v0[2], v0[3]); w.z = pk2(v1[0], v1[1]); w.w = pk2(v1[2], v1[3]);
;                                 *(u32x4*)cd = w;
;                             }
;                         }
;                     } else if (mode == 4) {
;                         if (colt < DFF && valid) {
;                             if (!samp && s >= SEQ - 2) { float* dst = ofp + ((size_t)b * 2 + (s - (SEQ - 2))) * DFF + col0; *(f32x4*)dst = v0; *(f32x4*)(dst + 4) = v1; }
;                             if (samp && s >= SSEQ - 2) { float* dst = ofs + ((size_t)(b - 16) * 2 + (s - (SSEQ - 2))) * DFF + col0; *(f32x4*)dst = v0; *(f32x4*)(dst + 4) = v1; }
;                         }
;                     }
;                     u32x4 w; w.x = pk2(v0[0], v0[1]); w.y = pk2(v0[2], v0[3]); w.z = pk2(v1[0], v1[1]); w.w = pk2(v1[2], v1[3]);
;                     *(u32x4*)(C + (size_t)row * ldc + col0) = w;
	v_cvt_pk_bf16_f32 v139, v50, v51
	global_store_dwordx4 v140, v[136:139], s[0:1] offset:256
	s_add_u32 s0, s0, s6
	s_addc_u32 s1, s1, 0
	s_add_u32 s16, s16, 0x10000
	s_addc_u32 s17, s17, 0
	global_store_dwordx4 v141, v[110:113], s[16:17] nt
	global_store_dwordx4 v141, v[44:47], s[16:17] offset:16 nt
	v_cvt_pk_bf16_f32 v132, v110, v111
	v_cvt_pk_bf16_f32 v133, v112, v113
	v_cvt_pk_bf16_f32 v134, v44, v45
	v_cvt_pk_bf16_f32 v135, v46, v47
	global_store_dwordx4 v140, v[132:135], s[0:1]
	global_store_dwordx4 v141, v[106:109], s[16:17] offset:512 nt
	global_store_dwordx4 v141, v[40:43], s[16:17] offset:528 nt
	v_cvt_pk_bf16_f32 v136, v106, v107
	v_cvt_pk_bf16_f32 v137, v108, v109
	v_cvt_pk_bf16_f32 v138, v40, v41
	v_cvt_pk_bf16_f32 v139, v42, v43
	global_store_dwordx4 v140, v[136:139], s[0:1] offset:256
	s_add_u32 s0, s0, s6
	s_addc_u32 s1, s1, 0
	s_add_u32 s16, s16, 0x10000
	s_addc_u32 s17, s17, 0
	global_store_dwordx4 v141, v[98:101], s[16:17] nt
	global_store_dwordx4 v141, v[32:35], s[16:17] offset:16 nt
	v_cvt_pk_bf16_f32 v132, v98, v99
	v_cvt_pk_bf16_f32 v133, v100, v101
	v_cvt_pk_bf16_f32 v134, v32, v33
	v_cvt_pk_bf16_f32 v135, v34, v35
	global_store_dwordx4 v140, v[132:135], s[0:1]
	global_store_dwordx4 v141, v[102:105], s[16:17] offset:512 nt
	global_store_dwordx4 v141, v[36:39], s[16:17] offset:528 nt
	v_cvt_pk_bf16_f32 v136, v102, v103
	v_cvt_pk_bf16_f32 v137, v104, v105
	v_cvt_pk_bf16_f32 v138, v36, v37
	v_cvt_pk_bf16_f32 v139, v38, v39
	global_store_dwordx4 v140, v[136:139], s[0:1] offset:256
	s_add_u32 s0, s30, s7
	s_addc_u32 s1, s31, 0
	s_add_u32 s16, s14, 0x80000
	s_addc_u32 s17, s15, 0
	global_store_dwordx4 v141, v[88:91], s[16:17] nt
	global_store_dwordx4 v141, v[24:27], s[16:17] offset:16 nt
	v_cvt_pk_bf16_f32 v132, v88, v89
	v_cvt_pk_bf16_f32 v133, v90, v91
	v_cvt_pk_bf16_f32 v134, v24, v25
	v_cvt_pk_bf16_f32 v135, v26, v27
	global_store_dwordx4 v140, v[132:135], s[0:1]
	global_store_dwordx4 v141, v[92:95], s[16:17] offset:512 nt
	global_store_dwordx4 v141, v[28:31], s[16:17] offset:528 nt
	v_cvt_pk_bf16_f32 v136, v92, v93
	v_cvt_pk_bf16_f32 v137, v94, v95
	v_cvt_pk_bf16_f32 v138, v28, v29
	v_cvt_pk_bf16_f32 v139, v30, v31
	global_store_dwordx4 v140, v[136:139], s[0:1] offset:256
	s_add_u32 s0, s0, s6
	s_addc_u32 s1, s1, 0
	s_add_u32 s16, s16, 0x10000
	s_addc_u32 s17, s17, 0
	global_store_dwordx4 v141, v[84:87], s[16:17] nt
	global_store_dwordx4 v141, v[20:23], s[16:17] offset:16 nt
	v_cvt_pk_bf16_f32 v132, v84, v85
	v_cvt_pk_bf16_f32 v133, v86, v87
	v_cvt_pk_bf16_f32 v134, v20, v21
	v_cvt_pk_bf16_f32 v135, v22, v23
	global_store_dwordx4 v140, v[132:135], s[0:1]
	global_store_dwordx4 v141, v[80:83], s[16:17] offset:512 nt
	global_store_dwordx4 v141, v[16:19], s[16:17] offset:528 nt
	v_cvt_pk_bf16_f32 v136, v80, v81
	v_cvt_pk_bf16_f32 v137, v82, v83
	v_cvt_pk_bf16_f32 v138, v16, v17
	v_cvt_pk_bf16_f32 v139, v18, v19
	global_store_dwordx4 v140, v[136:139], s[0:1] offset:256
	s_add_u32 s0, s0, s6
	s_addc_u32 s1, s1, 0
	s_add_u32 s16, s16, 0x10000
	s_addc_u32 s17, s17, 0
	global_store_dwordx4 v141, v[76:79], s[16:17] nt
	global_store_dwordx4 v141, v[12:15], s[16:17] offset:16 nt
	v_cvt_pk_bf16_f32 v132, v76, v77
	v_cvt_pk_bf16_f32 v133, v78, v79
	v_cvt_pk_bf16_f32 v134, v12, v13
	v_cvt_pk_bf16_f32 v135, v14, v15
	global_store_dwordx4 v140, v[132:135], s[0:1]
	global_store_dwordx4 v141, v[72:75], s[16:17] offset:512 nt
	global_store_dwordx4 v141, v[8:11], s[16:17] offset:528 nt
	v_cvt_pk_bf16_f32 v136, v72, v73
	v_cvt_pk_bf16_f32 v137, v74, v75
	v_cvt_pk_bf16_f32 v138, v8, v9
	v_cvt_pk_bf16_f32 v139, v10, v11
	global_store_dwordx4 v140, v[136:139], s[0:1] offset:256
	s_add_u32 s0, s0, s6
	s_addc_u32 s1, s1, 0
	s_add_u32 s16, s16, 0x10000
	s_addc_u32 s17, s17, 0
	global_store_dwordx4 v141, v[64:67], s[16:17] nt
	global_store_dwordx4 v141, v[0:3], s[16:17] offset:16 nt
	v_cvt_pk_bf16_f32 v132, v64, v65
	v_cvt_pk_bf16_f32 v133, v66, v67
	v_cvt_pk_bf16_f32 v134, v0, v1
	v_cvt_pk_bf16_f32 v135, v2, v3
	global_store_dwordx4 v140, v[132:135], s[0:1]
	global_store_dwordx4 v141, v[68:71], s[16:17] offset:512 nt
	global_store_dwordx4 v141, v[4:7], s[16:17] offset:528 nt
	v_cvt_pk_bf16_f32 v136, v68, v69
	v_cvt_pk_bf16_f32 v137, v70, v71
	v_cvt_pk_bf16_f32 v138, v4, v5
	v_cvt_pk_bf16_f32 v139, v6, v7
	global_store_dwordx4 v140, v[136:139], s[0:1] offset:256
	s_branch .LBB0_954
; DI unsigned pk2(float lo, float hi) { f32x2 v = {lo, hi}; bf16x2_t b = __builtin_convertvector(v, bf16x2_t); return __builtin_bit_cast(unsigned, b); }
;     __device__ __forceinline__ void operator()(const f32x4 (&acc)[2][2][4][2], const Unit& u, int wr, int wc, int fr, int fq) const {
;     ...
;                         if (region == 0) { const float sc = (mode == 2) ? QSCALE_DIFF : QSCALE_SB; v0 = v0 * sc; v1 = v1 * sc; }
;     ...
;                     u32x4 w; w.x = pk2(v0[0], v0[1]); w.y = pk2(v0[2], v0[3]); w.z = pk2(v1[0], v1[1]); w.w = pk2(v1[2], v1[3]);
;                     *(u32x4*)(C + (size_t)row * ldc + col0) = w;
.Lepi3_q:
	v_mul_f32_e32 v172, v146, v122
	v_mul_f32_e32 v173, v146, v123
	v_mul_f32_e32 v174, v146, v124
	v_mul_f32_e32 v175, v146, v125
	v_mul_f32_e32 v176, v146, v56
	v_mul_f32_e32 v177, v146, v57
	v_mul_f32_e32 v178, v146, v58
	v_mul_f32_e32 v179, v146, v59
	v_cvt_pk_bf16_f32 v132, v172, v173
	v_cvt_pk_bf16_f32 v133, v174, v175
	v_cvt_pk_bf16_f32 v134, v176, v177
	v_cvt_pk_bf16_f32 v135, v178, v179
	global_store_dwordx4 v140, v[132:135], s[0:1]
	v_mul_f32_e32 v180, v146, v126
	v_mul_f32_e32 v181, v146, v127
	v_mul_f32_e32 v182, v146, v128
	v_mul_f32_e32 v183, v146, v129
	v_mul_f32_e32 v184, v146, v60
	v_mul_f32_e32 v185, v146, v61
	v_mul_f32_e32 v186, v146, v62
	v_mul_f32_e32 v187, v146, v63
	v_cvt_pk_bf16_f32 v136, v180, v181
	v_cvt_pk_bf16_f32 v137, v182, v183
	v_cvt_pk_bf16_f32 v138, v184, v185
	v_cvt_pk_bf16_f32 v139, v186, v187
	global_store_dwordx4 v140, v[136:139], s[0:1] offset:256
	s_add_u32 s0, s0, s6
	s_addc_u32 s1, s1, 0
	v_mul_f32_e32 v172, v146, v118
	v_mul_f32_e32 v173, v146, v119
	v_mul_f32_e32 v174, v146, v120
	v_mul_f32_e32 v175, v146, v121
	v_mul_f32_e32 v176, v146, v52
	v_mul_f32_e32 v177, v146, v53
	v_mul_f32_e32 v178, v146, v54
	v_mul_f32_e32 v179, v146, v55
	v_cvt_pk_bf16_f32 v132, v172, v173
	v_cvt_pk_bf16_f32 v133, v174, v175
	v_cvt_pk_bf16_f32 v134, v176, v177
	v_cvt_pk_bf16_f32 v135, v178, v179
	global_store_dwordx4 v140, v[132:135], s[0:1]
	v_mul_f32_e32 v180, v146, v114
	v_mul_f32_e32 v181, v146, v115
	v_mul_f32_e32 v182, v146, v116
	v_mul_f32_e32 v183, v146, v117
	v_mul_f32_e32 v184, v146, v48
	v_mul_f32_e32 v185, v146, v49
	v_mul_f32_e32 v186, v146, v50
	v_mul_f32_e32 v187, v146, v51
	v_cvt_pk_bf16_f32 v136, v180, v181
	v_cvt_pk_bf16_f32 v137, v182, v183
	v_cvt_pk_bf16_f32 v138, v184, v185
	v_cvt_pk_bf16_f32 v139, v186, v187
	global_store_dwordx4 v140, v[136:139], s[0:1] offset:256
	s_add_u32 s0, s0, s6
	s_addc_u32 s1, s1, 0
	v_mul_f32_e32 v172, v146, v110
	v_mul_f32_e32 v173, v146, v111
	v_mul_f32_e32 v174, v146, v112
	v_mul_f32_e32 v175, v146, v113
	v_mul_f32_e32 v176, v146, v44
	v_mul_f32_e32 v177, v146, v45
	v_mul_f32_e32 v178, v146, v46
	v_mul_f32_e32 v179, v146, v47
	v_cvt_pk_bf16_f32 v132, v172, v173
	v_cvt_pk_bf16_f32 v133, v174, v175
	v_cvt_pk_bf16_f32 v134, v176, v177
	v_cvt_pk_bf16_f32 v135, v178, v179
	global_store_dwordx4 v140, v[132:135], s[0:1]
	v_mul_f32_e32 v180, v146, v106
	v_mul_f32_e32 v181, v146, v107
	v_mul_f32_e32 v182, v146, v108
	v_mul_f32_e32 v183, v146, v109
	v_mul_f32_e32 v184, v146, v40
	v_mul_f32_e32 v185, v146, v41
	v_mul_f32_e32 v186, v146, v42
	v_mul_f32_e32 v187, v146, v43
	v_cvt_pk_bf16_f32 v136, v180, v181
	v_cvt_pk_bf16_f32 v137, v182, v183
	v_cvt_pk_bf16_f32 v138, v184, v185
	v_cvt_pk_bf16_f32 v139, v186, v187
	global_store_dwordx4 v140, v[136:139], s[0:1] offset:256
	s_add_u32 s0, s0, s6
	s_addc_u32 s1, s1, 0
	v_mul_f32_e32 v172, v146, v98
	v_mul_f32_e32 v173, v146, v99
	v_mul_f32_e32 v174, v146, v100
	v_mul_f32_e32 v175, v146, v101
	v_mul_f32_e32 v176, v146, v32
	v_mul_f32_e32 v177, v146, v33
	v_mul_f32_e32 v178, v146, v34
	v_mul_f32_e32 v179, v146, v35
	v_cvt_pk_bf16_f32 v132, v172, v173
	v_cvt_pk_bf16_f32 v133, v174, v175
	v_cvt_pk_bf16_f32 v134, v176, v177
	v_cvt_pk_bf16_f32 v135, v178, v179
	global_store_dwordx4 v140, v[132:135], s[0:1]
	v_mul_f32_e32 v180, v146, v102
	v_mul_f32_e32 v181, v146, v103
	v_mul_f32_e32 v182, v146, v104
	v_mul_f32_e32 v183, v146, v105
	v_mul_f32_e32 v184, v146, v36
	v_mul_f32_e32 v185, v146, v37
	v_mul_f32_e32 v186, v146, v38
	v_mul_f32_e32 v187, v146, v39
	v_cvt_pk_bf16_f32 v136, v180, v181
	v_cvt_pk_bf16_f32 v137, v182, v183
	v_cvt_pk_bf16_f32 v138, v184, v185
	v_cvt_pk_bf16_f32 v139, v186, v187
	global_store_dwordx4 v140, v[136:139], s[0:1] offset:256
	s_add_u32 s0, s30, s7
	s_addc_u32 s1, s31, 0
	v_mul_f32_e32 v172, v146, v88
	v_mul_f32_e32 v173, v146, v89
	v_mul_f32_e32 v174, v146, v90
	v_mul_f32_e32 v175, v146, v91
	v_mul_f32_e32 v176, v146, v24
	v_mul_f32_e32 v177, v146, v25
	v_mul_f32_e32 v178, v146, v26
	v_mul_f32_e32 v179, v146, v27
	v_cvt_pk_bf16_f32 v132, v172, v173
	v_cvt_pk_bf16_f32 v133, v174, v175
	v_cvt_pk_bf16_f32 v134, v176, v177
	v_cvt_pk_bf16_f32 v135, v178, v179
	global_store_dwordx4 v140, v[132:135], s[0:1]
	v_mul_f32_e32 v180, v146, v92
	v_mul_f32_e32 v181, v146, v93
	v_mul_f32_e32 v182, v146, v94
	v_mul_f32_e32 v183, v146, v95
	v_mul_f32_e32 v184, v146, v28
	v_mul_f32_e32 v185, v146, v29
	v_mul_f32_e32 v186, v146, v30
	v_mul_f32_e32 v187, v146, v31
	v_cvt_pk_bf16_f32 v136, v180, v181
	v_cvt_pk_bf16_f32 v137, v182, v183
	v_cvt_pk_bf16_f32 v138, v184, v185
	v_cvt_pk_bf16_f32 v139, v186, v187
	global_store_dwordx4 v140, v[136:139], s[0:1] offset:256
	s_add_u32 s0, s0, s6
	s_addc_u32 s1, s1, 0
	v_mul_f32_e32 v172, v146, v84
	v_mul_f32_e32 v173, v146, v85
	v_mul_f32_e32 v174, v146, v86
	v_mul_f32_e32 v175, v146, v87
	v_mul_f32_e32 v176, v146, v20
	v_mul_f32_e32 v177, v146, v21
	v_mul_f32_e32 v178, v146, v22
	v_mul_f32_e32 v179, v146, v23
	v_cvt_pk_bf16_f32 v132, v172, v173
	v_cvt_pk_bf16_f32 v133, v174, v175
	v_cvt_pk_bf16_f32 v134, v176, v177
	v_cvt_pk_bf16_f32 v135, v178, v179
	global_store_dwordx4 v140, v[132:135], s[0:1]
	v_mul_f32_e32 v180, v146, v80
	v_mul_f32_e32 v181, v146, v81
	v_mul_f32_e32 v182, v146, v82
	v_mul_f32_e32 v183, v146, v83
	v_mul_f32_e32 v184, v146, v16
	v_mul_f32_e32 v185, v146, v17
	v_mul_f32_e32 v186, v146, v18
	v_mul_f32_e32 v187, v146, v19
	v_cvt_pk_bf16_f32 v136, v180, v181
	v_cvt_pk_bf16_f32 v137, v182, v183
	v_cvt_pk_bf16_f32 v138, v184, v185
	v_cvt_pk_bf16_f32 v139, v186, v187
	global_store_dwordx4 v140, v[136:139], s[0:1] offset:256
	s_add_u32 s0, s0, s6
	s_addc_u32 s1, s1, 0
; DI unsigned pk2(float lo, float hi) { f32x2 v = {lo, hi}; bf16x2_t b = __builtin_convertvector(v, bf16x2_t); return __builtin_bit_cast(unsigned, b); }
; DI float fexp2(float x) { return __builtin_amdgcn_exp2f(x); }
; DI float frcp(float x) { return __builtin_amdgcn_rcpf(x); }
;     __device__ __forceinline__ void operator()(const f32x4 (&acc)[2][2][4][2], const Unit& u, int wr, int wc, int fr, int fq) const {
;     ...
;                     if (mode == 1) {
; #pragma unroll
;                         for (int e = 0; e < 4; ++e) {
;                             { const float x = v0[e]; const float t = 0.7978845608028654f * (x + 0.044715f * x * x * x); v0[e] = x * frcp(1.f + fexp2(-2.f * LOG2E * t)); }
;                             { const float x = v1[e]; const float t = 0.7978845608028654f * (x + 0.044715f * x * x * x); v1[e] = x * frcp(1.f + fexp2(-2.f * LOG2E * t)); }
;                         }
;     ...
;                     u32x4 w; w.x = pk2(v0[0], v0[1]); w.y = pk2(v0[2], v0[3]); w.z = pk2(v1[0], v1[1]); w.w = pk2(v1[2], v1[3]);
;                     *(u32x4*)(C + (size_t)row * ldc + col0) = w;
	v_mul_f32_e32 v172, v146, v76
	v_mul_f32_e32 v173, v146, v77
	v_mul_f32_e32 v174, v146, v78
	v_mul_f32_e32 v175, v146, v79
	v_mul_f32_e32 v176, v146, v12
	v_mul_f32_e32 v177, v146, v13
	v_mul_f32_e32 v178, v146, v14
	v_mul_f32_e32 v179, v146, v15
	v_cvt_pk_bf16_f32 v132, v172, v173
	v_cvt_pk_bf16_f32 v133, v174, v175
	v_cvt_pk_bf16_f32 v134, v176, v177
	v_cvt_pk_bf16_f32 v135, v178, v179
	global_store_dwordx4 v140, v[132:135], s[0:1]
	v_mul_f32_e32 v180, v146, v72
	v_mul_f32_e32 v181, v146, v73
	v_mul_f32_e32 v182, v146, v74
	v_mul_f32_e32 v183, v146, v75
	v_mul_f32_e32 v184, v146, v8
	v_mul_f32_e32 v185, v146, v9
	v_mul_f32_e32 v186, v146, v10
	v_mul_f32_e32 v187, v146, v11
	v_cvt_pk_bf16_f32 v136, v180, v181
	v_cvt_pk_bf16_f32 v137, v182, v183
	v_cvt_pk_bf16_f32 v138, v184, v185
	v_cvt_pk_bf16_f32 v139, v186, v187
	global_store_dwordx4 v140, v[136:139], s[0:1] offset:256
	s_add_u32 s0, s0, s6
	s_addc_u32 s1, s1, 0
	v_mul_f32_e32 v172, v146, v64
	v_mul_f32_e32 v173, v146, v65
	v_mul_f32_e32 v174, v146, v66
	v_mul_f32_e32 v175, v146, v67
	v_mul_f32_e32 v176, v146, v0
	v_mul_f32_e32 v177, v146, v1
	v_mul_f32_e32 v178, v146, v2
	v_mul_f32_e32 v179, v146, v3
	v_cvt_pk_bf16_f32 v132, v172, v173
	v_cvt_pk_bf16_f32 v133, v174, v175
	v_cvt_pk_bf16_f32 v134, v176, v177
	v_cvt_pk_bf16_f32 v135, v178, v179
	global_store_dwordx4 v140, v[132:135], s[0:1]
	v_mul_f32_e32 v180, v146, v68
	v_mul_f32_e32 v181, v146, v69
	v_mul_f32_e32 v182, v146, v70
	v_mul_f32_e32 v183, v146, v71
	v_mul_f32_e32 v184, v146, v4
	v_mul_f32_e32 v185, v146, v5
	v_mul_f32_e32 v186, v146, v6
	v_mul_f32_e32 v187, v146, v7
	v_cvt_pk_bf16_f32 v136, v180, v181
	v_cvt_pk_bf16_f32 v137, v182, v183
	v_cvt_pk_bf16_f32 v138, v184, v185
	v_cvt_pk_bf16_f32 v139, v186, v187
	global_store_dwordx4 v140, v[136:139], s[0:1] offset:256
	s_branch .LBB0_954
.Lepi_fast1:
	s_lshl_b32 s6, s76, 8
	s_add_i32 s6, s6, s56
	v_or_b32_e32 v130, s6, v156
	v_lshl_or_b32 v131, s59, 8, v192
	v_mul_lo_u32 v140, v130, s70
	v_add_lshl_u32 v140, v140, v131, 1
	s_lshl_b32 s6, s70, 5
	s_lshl_b32 s7, s70, 8
	s_mov_b64 s[0:1], s[30:31]
	v_mul_f32_e32 v172, 0x3d372713, v122
	v_mul_f32_e32 v173, 0x3d372713, v123
	v_mul_f32_e32 v174, 0x3d372713, v124
	v_mul_f32_e32 v175, 0x3d372713, v125
	v_mul_f32_e32 v176, 0x3d372713, v56
	v_mul_f32_e32 v177, 0x3d372713, v57
	v_mul_f32_e32 v178, 0x3d372713, v58
	v_mul_f32_e32 v179, 0x3d372713, v59
	v_mul_f32_e32 v172, v122, v172
	v_mul_f32_e32 v173, v123, v173
	v_mul_f32_e32 v174, v124, v174
	v_mul_f32_e32 v175, v125, v175
	v_mul_f32_e32 v176, v56, v176
	v_mul_f32_e32 v177, v57, v177
	v_mul_f32_e32 v178, v58, v178
	v_mul_f32_e32 v179, v59, v179
	v_fma_f32 v172, v122, v172, v122
	v_fma_f32 v173, v123, v173, v123
	v_fma_f32 v174, v124, v174, v124
	v_fma_f32 v175, v125, v175, v125
	v_fma_f32 v176, v56, v176, v56
	v_fma_f32 v177, v57, v177, v57
	v_fma_f32 v178, v58, v178, v58
	v_fma_f32 v179, v59, v179, v59
	v_mul_f32_e32 v172, 0x3f4c422a, v172
	v_mul_f32_e32 v173, 0x3f4c422a, v173
	v_mul_f32_e32 v174, 0x3f4c422a, v174
	v_mul_f32_e32 v175, 0x3f4c422a, v175
	v_mul_f32_e32 v176, 0x3f4c422a, v176
	v_mul_f32_e32 v177, 0x3f4c422a, v177
	v_mul_f32_e32 v178, 0x3f4c422a, v178
	v_mul_f32_e32 v179, 0x3f4c422a, v179
	v_mul_f32_e32 v172, 0xc038aa3b, v172
	v_mul_f32_e32 v173, 0xc038aa3b, v173
	v_mul_f32_e32 v174, 0xc038aa3b, v174
	v_mul_f32_e32 v175, 0xc038aa3b, v175
	v_mul_f32_e32 v176, 0xc038aa3b, v176
	v_mul_f32_e32 v177, 0xc038aa3b, v177
	v_mul_f32_e32 v178, 0xc038aa3b, v178
	v_mul_f32_e32 v179, 0xc038aa3b, v179
	v_exp_f32_e32 v172, v172
	v_exp_f32_e32 v173, v173
	v_exp_f32_e32 v174, v174
	v_exp_f32_e32 v175, v175
	v_exp_f32_e32 v176, v176
	v_exp_f32_e32 v177, v177
	v_exp_f32_e32 v178, v178
	v_exp_f32_e32 v179, v179
	v_add_f32_e32 v172, 1.0, v172
	v_add_f32_e32 v173, 1.0, v173
	v_add_f32_e32 v174, 1.0, v174
	v_add_f32_e32 v175, 1.0, v175
	v_add_f32_e32 v176, 1.0, v176
	v_add_f32_e32 v177, 1.0, v177
	v_add_f32_e32 v178, 1.0, v178
	v_add_f32_e32 v179, 1.0, v179
	v_rcp_f32_e32 v172, v172
	v_rcp_f32_e32 v173, v173
	v_rcp_f32_e32 v174, v174
	v_rcp_f32_e32 v175, v175
	v_rcp_f32_e32 v176, v176
	v_rcp_f32_e32 v177, v177
	v_rcp_f32_e32 v178, v178
	v_rcp_f32_e32 v179, v179
	v_mul_f32_e32 v172, v122, v172
	v_mul_f32_e32 v173, v123, v173
	v_mul_f32_e32 v174, v124, v174
	v_mul_f32_e32 v175, v125, v175
	v_mul_f32_e32 v176, v56, v176
	v_mul_f32_e32 v177, v57, v177
	v_mul_f32_e32 v178, v58, v178
	v_mul_f32_e32 v179, v59, v179
	v_cvt_pk_bf16_f32 v132, v172, v173
	v_cvt_pk_bf16_f32 v133, v174, v175
	v_cvt_pk_bf16_f32 v134, v176, v177
	v_cvt_pk_bf16_f32 v135, v178, v179
	global_store_dwordx4 v140, v[132:135], s[0:1]
	v_mul_f32_e32 v180, 0x3d372713, v126
	v_mul_f32_e32 v181, 0x3d372713, v127
	v_mul_f32_e32 v182, 0x3d372713, v128
	v_mul_f32_e32 v183, 0x3d372713, v129
	v_mul_f32_e32 v184, 0x3d372713, v60
	v_mul_f32_e32 v185, 0x3d372713, v61
	v_mul_f32_e32 v186, 0x3d372713, v62
	v_mul_f32_e32 v187, 0x3d372713, v63
	v_mul_f32_e32 v180, v126, v180
	v_mul_f32_e32 v181, v127, v181
	v_mul_f32_e32 v182, v128, v182
	v_mul_f32_e32 v183, v129, v183
	v_mul_f32_e32 v184, v60, v184
	v_mul_f32_e32 v185, v61, v185
	v_mul_f32_e32 v186, v62, v186
	v_mul_f32_e32 v187, v63, v187
	v_fma_f32 v180, v126, v180, v126
	v_fma_f32 v181, v127, v181, v127
	v_fma_f32 v182, v128, v182, v128
	v_fma_f32 v183, v129, v183, v129
	v_fma_f32 v184, v60, v184, v60
	v_fma_f32 v185, v61, v185, v61
	v_fma_f32 v186, v62, v186, v62
	v_fma_f32 v187, v63, v187, v63
	v_mul_f32_e32 v180, 0x3f4c422a, v180
	v_mul_f32_e32 v181, 0x3f4c422a, v181
	v_mul_f32_e32 v182, 0x3f4c422a, v182
	v_mul_f32_e32 v183, 0x3f4c422a, v183
	v_mul_f32_e32 v184, 0x3f4c422a, v184
; DI unsigned pk2(float lo, float hi) { f32x2 v = {lo, hi}; bf16x2_t b = __builtin_convertvector(v, bf16x2_t); return __builtin_bit_cast(unsigned, b); }
; DI float fexp2(float x) { return __builtin_amdgcn_exp2f(x); }
; DI float frcp(float x) { return __builtin_amdgcn_rcpf(x); }
;     __device__ __forceinline__ void operator()(const f32x4 (&acc)[2][2][4][2], const Unit& u, int wr, int wc, int fr, int fq) const {
;     ...
;                     if (mode == 1) {
; #pragma unroll
;                         for (int e = 0; e < 4; ++e) {
;                             { const float x = v0[e]; const float t = 0.7978845608028654f * (x + 0.044715f * x * x * x); v0[e] = x * frcp(1.f + fexp2(-2.f * LOG2E * t)); }
;                             { const float x = v1[e]; const float t = 0.7978845608028654f * (x + 0.044715f * x * x * x); v1[e] = x * frcp(1.f + fexp2(-2.f * LOG2E * t)); }
;                         }
;     ...
;                     u32x4 w; w.x = pk2(v0[0], v0[1]); w.y = pk2(v0[2], v0[3]); w.z = pk2(v1[0], v1[1]); w.w = pk2(v1[2], v1[3]);
;                     *(u32x4*)(C + (size_t)row * ldc + col0) = w;
	v_mul_f32_e32 v185, 0x3f4c422a, v185
	v_mul_f32_e32 v186, 0x3f4c422a, v186
	v_mul_f32_e32 v187, 0x3f4c422a, v187
	v_mul_f32_e32 v180, 0xc038aa3b, v180
	v_mul_f32_e32 v181, 0xc038aa3b, v181
	v_mul_f32_e32 v182, 0xc038aa3b, v182
	v_mul_f32_e32 v183, 0xc038aa3b, v183
	v_mul_f32_e32 v184, 0xc038aa3b, v184
	v_mul_f32_e32 v185, 0xc038aa3b, v185
	v_mul_f32_e32 v186, 0xc038aa3b, v186
	v_mul_f32_e32 v187, 0xc038aa3b, v187
	v_exp_f32_e32 v180, v180
	v_exp_f32_e32 v181, v181
	v_exp_f32_e32 v182, v182
	v_exp_f32_e32 v183, v183
	v_exp_f32_e32 v184, v184
	v_exp_f32_e32 v185, v185
	v_exp_f32_e32 v186, v186
	v_exp_f32_e32 v187, v187
	v_add_f32_e32 v180, 1.0, v180
	v_add_f32_e32 v181, 1.0, v181
	v_add_f32_e32 v182, 1.0, v182
	v_add_f32_e32 v183, 1.0, v183
	v_add_f32_e32 v184, 1.0, v184
	v_add_f32_e32 v185, 1.0, v185
	v_add_f32_e32 v186, 1.0, v186
	v_add_f32_e32 v187, 1.0, v187
	v_rcp_f32_e32 v180, v180
	v_rcp_f32_e32 v181, v181
	v_rcp_f32_e32 v182, v182
	v_rcp_f32_e32 v183, v183
	v_rcp_f32_e32 v184, v184
	v_rcp_f32_e32 v185, v185
	v_rcp_f32_e32 v186, v186
	v_rcp_f32_e32 v187, v187
	v_mul_f32_e32 v180, v126, v180
	v_mul_f32_e32 v181, v127, v181
	v_mul_f32_e32 v182, v128, v182
	v_mul_f32_e32 v183, v129, v183
	v_mul_f32_e32 v184, v60, v184
	v_mul_f32_e32 v185, v61, v185
	v_mul_f32_e32 v186, v62, v186
	v_mul_f32_e32 v187, v63, v187
	v_cvt_pk_bf16_f32 v136, v180, v181
	v_cvt_pk_bf16_f32 v137, v182, v183
	v_cvt_pk_bf16_f32 v138, v184, v185
	v_cvt_pk_bf16_f32 v139, v186, v187
	global_store_dwordx4 v140, v[136:139], s[0:1] offset:256
	s_add_u32 s0, s0, s6
	s_addc_u32 s1, s1, 0
	v_mul_f32_e32 v172, 0x3d372713, v118
	v_mul_f32_e32 v173, 0x3d372713, v119
	v_mul_f32_e32 v174, 0x3d372713, v120
	v_mul_f32_e32 v175, 0x3d372713, v121
	v_mul_f32_e32 v176, 0x3d372713, v52
	v_mul_f32_e32 v177, 0x3d372713, v53
	v_mul_f32_e32 v178, 0x3d372713, v54
	v_mul_f32_e32 v179, 0x3d372713, v55
	v_mul_f32_e32 v172, v118, v172
	v_mul_f32_e32 v173, v119, v173
	v_mul_f32_e32 v174, v120, v174
	v_mul_f32_e32 v175, v121, v175
	v_mul_f32_e32 v176, v52, v176
	v_mul_f32_e32 v177, v53, v177
	v_mul_f32_e32 v178, v54, v178
	v_mul_f32_e32 v179, v55, v179
	v_fma_f32 v172, v118, v172, v118
	v_fma_f32 v173, v119, v173, v119
	v_fma_f32 v174, v120, v174, v120
	v_fma_f32 v175, v121, v175, v121
	v_fma_f32 v176, v52, v176, v52
	v_fma_f32 v177, v53, v177, v53
	v_fma_f32 v178, v54, v178, v54
	v_fma_f32 v179, v55, v179, v55
	v_mul_f32_e32 v172, 0x3f4c422a, v172
	v_mul_f32_e32 v173, 0x3f4c422a, v173
	v_mul_f32_e32 v174, 0x3f4c422a, v174
	v_mul_f32_e32 v175, 0x3f4c422a, v175
	v_mul_f32_e32 v176, 0x3f4c422a, v176
	v_mul_f32_e32 v177, 0x3f4c422a, v177
	v_mul_f32_e32 v178, 0x3f4c422a, v178
	v_mul_f32_e32 v179, 0x3f4c422a, v179
	v_mul_f32_e32 v172, 0xc038aa3b, v172
	v_mul_f32_e32 v173, 0xc038aa3b, v173
	v_mul_f32_e32 v174, 0xc038aa3b, v174
	v_mul_f32_e32 v175, 0xc038aa3b, v175
	v_mul_f32_e32 v176, 0xc038aa3b, v176
	v_mul_f32_e32 v177, 0xc038aa3b, v177
	v_mul_f32_e32 v178, 0xc038aa3b, v178
	v_mul_f32_e32 v179, 0xc038aa3b, v179
	v_exp_f32_e32 v172, v172
	v_exp_f32_e32 v173, v173
	v_exp_f32_e32 v174, v174
	v_exp_f32_e32 v175, v175
	v_exp_f32_e32 v176, v176
	v_exp_f32_e32 v177, v177
	v_exp_f32_e32 v178, v178
	v_exp_f32_e32 v179, v179
	v_add_f32_e32 v172, 1.0, v172
	v_add_f32_e32 v173, 1.0, v173
	v_add_f32_e32 v174, 1.0, v174
	v_add_f32_e32 v175, 1.0, v175
	v_add_f32_e32 v176, 1.0, v176
	v_add_f32_e32 v177, 1.0, v177
	v_add_f32_e32 v178, 1.0, v178
	v_add_f32_e32 v179, 1.0, v179
	v_rcp_f32_e32 v172, v172
	v_rcp_f32_e32 v173, v173
	v_rcp_f32_e32 v174, v174
	v_rcp_f32_e32 v175, v175
	v_rcp_f32_e32 v176, v176
	v_rcp_f32_e32 v177, v177
	v_rcp_f32_e32 v178, v178
	v_rcp_f32_e32 v179, v179
	v_mul_f32_e32 v172, v118, v172
	v_mul_f32_e32 v173, v119, v173
	v_mul_f32_e32 v174, v120, v174
	v_mul_f32_e32 v175, v121, v175
	v_mul_f32_e32 v176, v52, v176
	v_mul_f32_e32 v177, v53, v177
	v_mul_f32_e32 v178, v54, v178
	v_mul_f32_e32 v179, v55, v179
	v_cvt_pk_bf16_f32 v132, v172, v173
	v_cvt_pk_bf16_f32 v133, v174, v175
	v_cvt_pk_bf16_f32 v134, v176, v177
	v_cvt_pk_bf16_f32 v135, v178, v179
	global_store_dwordx4 v140, v[132:135], s[0:1]
	v_mul_f32_e32 v180, 0x3d372713, v114
	v_mul_f32_e32 v181, 0x3d372713, v115
	v_mul_f32_e32 v182, 0x3d372713, v116
	v_mul_f32_e32 v183, 0x3d372713, v117
	v_mul_f32_e32 v184, 0x3d372713, v48
	v_mul_f32_e32 v185, 0x3d372713, v49
	v_mul_f32_e32 v186, 0x3d372713, v50
	v_mul_f32_e32 v187, 0x3d372713, v51
	v_mul_f32_e32 v180, v114, v180
	v_mul_f32_e32 v181, v115, v181
	v_mul_f32_e32 v182, v116, v182
	v_mul_f32_e32 v183, v117, v183
	v_mul_f32_e32 v184, v48, v184
	v_mul_f32_e32 v185, v49, v185
	v_mul_f32_e32 v186, v50, v186
	v_mul_f32_e32 v187, v51, v187
	v_fma_f32 v180, v114, v180, v114
	v_fma_f32 v181, v115, v181, v115
	v_fma_f32 v182, v116, v182, v116
	v_fma_f32 v183, v117, v183, v117
	v_fma_f32 v184, v48, v184, v48
	v_fma_f32 v185, v49, v185, v49
	v_fma_f32 v186, v50, v186, v50
	v_fma_f32 v187, v51, v187, v51
	v_mul_f32_e32 v180, 0x3f4c422a, v180
	v_mul_f32_e32 v181, 0x3f4c422a, v181
	v_mul_f32_e32 v182, 0x3f4c422a, v182
	v_mul_f32_e32 v183, 0x3f4c422a, v183
	v_mul_f32_e32 v184, 0x3f4c422a, v184
	v_mul_f32_e32 v185, 0x3f4c422a, v185
	v_mul_f32_e32 v186, 0x3f4c422a, v186
	v_mul_f32_e32 v187, 0x3f4c422a, v187
	v_mul_f32_e32 v180, 0xc038aa3b, v180
	v_mul_f32_e32 v181, 0xc038aa3b, v181
	v_mul_f32_e32 v182, 0xc038aa3b, v182
	v_mul_f32_e32 v183, 0xc038aa3b, v183
	v_mul_f32_e32 v184, 0xc038aa3b, v184
	v_mul_f32_e32 v185, 0xc038aa3b, v185
	v_mul_f32_e32 v186, 0xc038aa3b, v186
	v_mul_f32_e32 v187, 0xc038aa3b, v187
	v_exp_f32_e32 v180, v180
	v_exp_f32_e32 v181, v181
	v_exp_f32_e32 v182, v182
	v_exp_f32_e32 v183, v183
; DI unsigned pk2(float lo, float hi) { f32x2 v = {lo, hi}; bf16x2_t b = __builtin_convertvector(v, bf16x2_t); return __builtin_bit_cast(unsigned, b); }
; DI float fexp2(float x) { return __builtin_amdgcn_exp2f(x); }
; DI float frcp(float x) { return __builtin_amdgcn_rcpf(x); }
;     __device__ __forceinline__ void operator()(const f32x4 (&acc)[2][2][4][2], const Unit& u, int wr, int wc, int fr, int fq) const {
;     ...
;                     if (mode == 1) {
; #pragma unroll
;                         for (int e = 0; e < 4; ++e) {
;                             { const float x = v0[e]; const float t = 0.7978845608028654f * (x + 0.044715f * x * x * x); v0[e] = x * frcp(1.f + fexp2(-2.f * LOG2E * t)); }
;                             { const float x = v1[e]; const float t = 0.7978845608028654f * (x + 0.044715f * x * x * x); v1[e] = x * frcp(1.f + fexp2(-2.f * LOG2E * t)); }
;                         }
;     ...
;                     u32x4 w; w.x = pk2(v0[0], v0[1]); w.y = pk2(v0[2], v0[3]); w.z = pk2(v1[0], v1[1]); w.w = pk2(v1[2], v1[3]);
;                     *(u32x4*)(C + (size_t)row * ldc + col0) = w;
	v_exp_f32_e32 v184, v184
	v_exp_f32_e32 v185, v185
	v_exp_f32_e32 v186, v186
	v_exp_f32_e32 v187, v187
	v_add_f32_e32 v180, 1.0, v180
	v_add_f32_e32 v181, 1.0, v181
	v_add_f32_e32 v182, 1.0, v182
	v_add_f32_e32 v183, 1.0, v183
	v_add_f32_e32 v184, 1.0, v184
	v_add_f32_e32 v185, 1.0, v185
	v_add_f32_e32 v186, 1.0, v186
	v_add_f32_e32 v187, 1.0, v187
	v_rcp_f32_e32 v180, v180
	v_rcp_f32_e32 v181, v181
	v_rcp_f32_e32 v182, v182
	v_rcp_f32_e32 v183, v183
	v_rcp_f32_e32 v184, v184
	v_rcp_f32_e32 v185, v185
	v_rcp_f32_e32 v186, v186
	v_rcp_f32_e32 v187, v187
	v_mul_f32_e32 v180, v114, v180
	v_mul_f32_e32 v181, v115, v181
	v_mul_f32_e32 v182, v116, v182
	v_mul_f32_e32 v183, v117, v183
	v_mul_f32_e32 v184, v48, v184
	v_mul_f32_e32 v185, v49, v185
	v_mul_f32_e32 v186, v50, v186
	v_mul_f32_e32 v187, v51, v187
	v_cvt_pk_bf16_f32 v136, v180, v181
	v_cvt_pk_bf16_f32 v137, v182, v183
	v_cvt_pk_bf16_f32 v138, v184, v185
	v_cvt_pk_bf16_f32 v139, v186, v187
	global_store_dwordx4 v140, v[136:139], s[0:1] offset:256
	s_add_u32 s0, s0, s6
	s_addc_u32 s1, s1, 0
	v_mul_f32_e32 v172, 0x3d372713, v110
	v_mul_f32_e32 v173, 0x3d372713, v111
	v_mul_f32_e32 v174, 0x3d372713, v112
	v_mul_f32_e32 v175, 0x3d372713, v113
	v_mul_f32_e32 v176, 0x3d372713, v44
	v_mul_f32_e32 v177, 0x3d372713, v45
	v_mul_f32_e32 v178, 0x3d372713, v46
	v_mul_f32_e32 v179, 0x3d372713, v47
	v_mul_f32_e32 v172, v110, v172
	v_mul_f32_e32 v173, v111, v173
	v_mul_f32_e32 v174, v112, v174
	v_mul_f32_e32 v175, v113, v175
	v_mul_f32_e32 v176, v44, v176
	v_mul_f32_e32 v177, v45, v177
	v_mul_f32_e32 v178, v46, v178
	v_mul_f32_e32 v179, v47, v179
	v_fma_f32 v172, v110, v172, v110
	v_fma_f32 v173, v111, v173, v111
	v_fma_f32 v174, v112, v174, v112
	v_fma_f32 v175, v113, v175, v113
	v_fma_f32 v176, v44, v176, v44
	v_fma_f32 v177, v45, v177, v45
	v_fma_f32 v178, v46, v178, v46
	v_fma_f32 v179, v47, v179, v47
	v_mul_f32_e32 v172, 0x3f4c422a, v172
	v_mul_f32_e32 v173, 0x3f4c422a, v173
	v_mul_f32_e32 v174, 0x3f4c422a, v174
	v_mul_f32_e32 v175, 0x3f4c422a, v175
	v_mul_f32_e32 v176, 0x3f4c422a, v176
	v_mul_f32_e32 v177, 0x3f4c422a, v177
	v_mul_f32_e32 v178, 0x3f4c422a, v178
	v_mul_f32_e32 v179, 0x3f4c422a, v179
	v_mul_f32_e32 v172, 0xc038aa3b, v172
	v_mul_f32_e32 v173, 0xc038aa3b, v173
	v_mul_f32_e32 v174, 0xc038aa3b, v174
	v_mul_f32_e32 v175, 0xc038aa3b, v175
	v_mul_f32_e32 v176, 0xc038aa3b, v176
	v_mul_f32_e32 v177, 0xc038aa3b, v177
	v_mul_f32_e32 v178, 0xc038aa3b, v178
	v_mul_f32_e32 v179, 0xc038aa3b, v179
	v_exp_f32_e32 v172, v172
	v_exp_f32_e32 v173, v173
	v_exp_f32_e32 v174, v174
	v_exp_f32_e32 v175, v175
	v_exp_f32_e32 v176, v176
	v_exp_f32_e32 v177, v177
	v_exp_f32_e32 v178, v178
	v_exp_f32_e32 v179, v179
	v_add_f32_e32 v172, 1.0, v172
	v_add_f32_e32 v173, 1.0, v173
	v_add_f32_e32 v174, 1.0, v174
	v_add_f32_e32 v175, 1.0, v175
	v_add_f32_e32 v176, 1.0, v176
	v_add_f32_e32 v177, 1.0, v177
	v_add_f32_e32 v178, 1.0, v178
	v_add_f32_e32 v179, 1.0, v179
	v_rcp_f32_e32 v172, v172
	v_rcp_f32_e32 v173, v173
	v_rcp_f32_e32 v174, v174
	v_rcp_f32_e32 v175, v175
	v_rcp_f32_e32 v176, v176
	v_rcp_f32_e32 v177, v177
	v_rcp_f32_e32 v178, v178
	v_rcp_f32_e32 v179, v179
	v_mul_f32_e32 v172, v110, v172
	v_mul_f32_e32 v173, v111, v173
	v_mul_f32_e32 v174, v112, v174
	v_mul_f32_e32 v175, v113, v175
	v_mul_f32_e32 v176, v44, v176
	v_mul_f32_e32 v177, v45, v177
	v_mul_f32_e32 v178, v46, v178
	v_mul_f32_e32 v179, v47, v179
	v_cvt_pk_bf16_f32 v132, v172, v173
	v_cvt_pk_bf16_f32 v133, v174, v175
	v_cvt_pk_bf16_f32 v134, v176, v177
	v_cvt_pk_bf16_f32 v135, v178, v179
	global_store_dwordx4 v140, v[132:135], s[0:1]
	v_mul_f32_e32 v180, 0x3d372713, v106
	v_mul_f32_e32 v181, 0x3d372713, v107
	v_mul_f32_e32 v182, 0x3d372713, v108
	v_mul_f32_e32 v183, 0x3d372713, v109
	v_mul_f32_e32 v184, 0x3d372713, v40
	v_mul_f32_e32 v185, 0x3d372713, v41
	v_mul_f32_e32 v186, 0x3d372713, v42
	v_mul_f32_e32 v187, 0x3d372713, v43
	v_mul_f32_e32 v180, v106, v180
	v_mul_f32_e32 v181, v107, v181
	v_mul_f32_e32 v182, v108, v182
	v_mul_f32_e32 v183, v109, v183
	v_mul_f32_e32 v184, v40, v184
	v_mul_f32_e32 v185, v41, v185
	v_mul_f32_e32 v186, v42, v186
	v_mul_f32_e32 v187, v43, v187
	v_fma_f32 v180, v106, v180, v106
	v_fma_f32 v181, v107, v181, v107
	v_fma_f32 v182, v108, v182, v108
	v_fma_f32 v183, v109, v183, v109
	v_fma_f32 v184, v40, v184, v40
	v_fma_f32 v185, v41, v185, v41
	v_fma_f32 v186, v42, v186, v42
	v_fma_f32 v187, v43, v187, v43
	v_mul_f32_e32 v180, 0x3f4c422a, v180
	v_mul_f32_e32 v181, 0x3f4c422a, v181
	v_mul_f32_e32 v182, 0x3f4c422a, v182
	v_mul_f32_e32 v183, 0x3f4c422a, v183
	v_mul_f32_e32 v184, 0x3f4c422a, v184
	v_mul_f32_e32 v185, 0x3f4c422a, v185
	v_mul_f32_e32 v186, 0x3f4c422a, v186
	v_mul_f32_e32 v187, 0x3f4c422a, v187
	v_mul_f32_e32 v180, 0xc038aa3b, v180
	v_mul_f32_e32 v181, 0xc038aa3b, v181
	v_mul_f32_e32 v182, 0xc038aa3b, v182
	v_mul_f32_e32 v183, 0xc038aa3b, v183
	v_mul_f32_e32 v184, 0xc038aa3b, v184
	v_mul_f32_e32 v185, 0xc038aa3b, v185
	v_mul_f32_e32 v186, 0xc038aa3b, v186
	v_mul_f32_e32 v187, 0xc038aa3b, v187
	v_exp_f32_e32 v180, v180
	v_exp_f32_e32 v181, v181
	v_exp_f32_e32 v182, v182
	v_exp_f32_e32 v183, v183
	v_exp_f32_e32 v184, v184
	v_exp_f32_e32 v185, v185
	v_exp_f32_e32 v186, v186
	v_exp_f32_e32 v187, v187
	v_add_f32_e32 v180, 1.0, v180
	v_add_f32_e32 v181, 1.0, v181
	v_add_f32_e32 v182, 1.0, v182
	v_add_f32_e32 v183, 1.0, v183
	v_add_f32_e32 v184, 1.0, v184
	v_add_f32_e32 v185, 1.0, v185
	v_add_f32_e32 v186, 1.0, v186
	v_add_f32_e32 v187, 1.0, v187
	v_rcp_f32_e32 v180, v180
	v_rcp_f32_e32 v181, v181
	v_rcp_f32_e32 v182, v182
	v_rcp_f32_e32 v183, v183
	v_rcp_f32_e32 v184, v184
	v_rcp_f32_e32 v185, v185
	v_rcp_f32_e32 v186, v186
; DI unsigned pk2(float lo, float hi) { f32x2 v = {lo, hi}; bf16x2_t b = __builtin_convertvector(v, bf16x2_t); return __builtin_bit_cast(unsigned, b); }
; DI float fexp2(float x) { return __builtin_amdgcn_exp2f(x); }
; DI float frcp(float x) { return __builtin_amdgcn_rcpf(x); }
;     __device__ __forceinline__ void operator()(const f32x4 (&acc)[2][2][4][2], const Unit& u, int wr, int wc, int fr, int fq) const {
;     ...
;                     if (mode == 1) {
; #pragma unroll
;                         for (int e = 0; e < 4; ++e) {
;                             { const float x = v0[e]; const float t = 0.7978845608028654f * (x + 0.044715f * x * x * x); v0[e] = x * frcp(1.f + fexp2(-2.f * LOG2E * t)); }
;                             { const float x = v1[e]; const float t = 0.7978845608028654f * (x + 0.044715f * x * x * x); v1[e] = x * frcp(1.f + fexp2(-2.f * LOG2E * t)); }
;                         }
;     ...
;                     u32x4 w; w.x = pk2(v0[0], v0[1]); w.y = pk2(v0[2], v0[3]); w.z = pk2(v1[0], v1[1]); w.w = pk2(v1[2], v1[3]);
;                     *(u32x4*)(C + (size_t)row * ldc + col0) = w;
	v_rcp_f32_e32 v187, v187
	v_mul_f32_e32 v180, v106, v180
	v_mul_f32_e32 v181, v107, v181
	v_mul_f32_e32 v182, v108, v182
	v_mul_f32_e32 v183, v109, v183
	v_mul_f32_e32 v184, v40, v184
	v_mul_f32_e32 v185, v41, v185
	v_mul_f32_e32 v186, v42, v186
	v_mul_f32_e32 v187, v43, v187
	v_cvt_pk_bf16_f32 v136, v180, v181
	v_cvt_pk_bf16_f32 v137, v182, v183
	v_cvt_pk_bf16_f32 v138, v184, v185
	v_cvt_pk_bf16_f32 v139, v186, v187
	global_store_dwordx4 v140, v[136:139], s[0:1] offset:256
	s_add_u32 s0, s0, s6
	s_addc_u32 s1, s1, 0
	v_mul_f32_e32 v172, 0x3d372713, v98
	v_mul_f32_e32 v173, 0x3d372713, v99
	v_mul_f32_e32 v174, 0x3d372713, v100
	v_mul_f32_e32 v175, 0x3d372713, v101
	v_mul_f32_e32 v176, 0x3d372713, v32
	v_mul_f32_e32 v177, 0x3d372713, v33
	v_mul_f32_e32 v178, 0x3d372713, v34
	v_mul_f32_e32 v179, 0x3d372713, v35
	v_mul_f32_e32 v172, v98, v172
	v_mul_f32_e32 v173, v99, v173
	v_mul_f32_e32 v174, v100, v174
	v_mul_f32_e32 v175, v101, v175
	v_mul_f32_e32 v176, v32, v176
	v_mul_f32_e32 v177, v33, v177
	v_mul_f32_e32 v178, v34, v178
	v_mul_f32_e32 v179, v35, v179
	v_fma_f32 v172, v98, v172, v98
	v_fma_f32 v173, v99, v173, v99
	v_fma_f32 v174, v100, v174, v100
	v_fma_f32 v175, v101, v175, v101
	v_fma_f32 v176, v32, v176, v32
	v_fma_f32 v177, v33, v177, v33
	v_fma_f32 v178, v34, v178, v34
	v_fma_f32 v179, v35, v179, v35
	v_mul_f32_e32 v172, 0x3f4c422a, v172
	v_mul_f32_e32 v173, 0x3f4c422a, v173
	v_mul_f32_e32 v174, 0x3f4c422a, v174
	v_mul_f32_e32 v175, 0x3f4c422a, v175
	v_mul_f32_e32 v176, 0x3f4c422a, v176
	v_mul_f32_e32 v177, 0x3f4c422a, v177
	v_mul_f32_e32 v178, 0x3f4c422a, v178
	v_mul_f32_e32 v179, 0x3f4c422a, v179
	v_mul_f32_e32 v172, 0xc038aa3b, v172
	v_mul_f32_e32 v173, 0xc038aa3b, v173
	v_mul_f32_e32 v174, 0xc038aa3b, v174
	v_mul_f32_e32 v175, 0xc038aa3b, v175
	v_mul_f32_e32 v176, 0xc038aa3b, v176
	v_mul_f32_e32 v177, 0xc038aa3b, v177
	v_mul_f32_e32 v178, 0xc038aa3b, v178
	v_mul_f32_e32 v179, 0xc038aa3b, v179
	v_exp_f32_e32 v172, v172
	v_exp_f32_e32 v173, v173
	v_exp_f32_e32 v174, v174
	v_exp_f32_e32 v175, v175
	v_exp_f32_e32 v176, v176
	v_exp_f32_e32 v177, v177
	v_exp_f32_e32 v178, v178
	v_exp_f32_e32 v179, v179
	v_add_f32_e32 v172, 1.0, v172
	v_add_f32_e32 v173, 1.0, v173
	v_add_f32_e32 v174, 1.0, v174
	v_add_f32_e32 v175, 1.0, v175
	v_add_f32_e32 v176, 1.0, v176
	v_add_f32_e32 v177, 1.0, v177
	v_add_f32_e32 v178, 1.0, v178
	v_add_f32_e32 v179, 1.0, v179
	v_rcp_f32_e32 v172, v172
	v_rcp_f32_e32 v173, v173
	v_rcp_f32_e32 v174, v174
	v_rcp_f32_e32 v175, v175
	v_rcp_f32_e32 v176, v176
	v_rcp_f32_e32 v177, v177
	v_rcp_f32_e32 v178, v178
	v_rcp_f32_e32 v179, v179
	v_mul_f32_e32 v172, v98, v172
	v_mul_f32_e32 v173, v99, v173
	v_mul_f32_e32 v174, v100, v174
	v_mul_f32_e32 v175, v101, v175
	v_mul_f32_e32 v176, v32, v176
	v_mul_f32_e32 v177, v33, v177
	v_mul_f32_e32 v178, v34, v178
	v_mul_f32_e32 v179, v35, v179
	v_cvt_pk_bf16_f32 v132, v172, v173
	v_cvt_pk_bf16_f32 v133, v174, v175
	v_cvt_pk_bf16_f32 v134, v176, v177
	v_cvt_pk_bf16_f32 v135, v178, v179
	global_store_dwordx4 v140, v[132:135], s[0:1]
	v_mul_f32_e32 v180, 0x3d372713, v102
	v_mul_f32_e32 v181, 0x3d372713, v103
	v_mul_f32_e32 v182, 0x3d372713, v104
	v_mul_f32_e32 v183, 0x3d372713, v105
	v_mul_f32_e32 v184, 0x3d372713, v36
	v_mul_f32_e32 v185, 0x3d372713, v37
	v_mul_f32_e32 v186, 0x3d372713, v38
	v_mul_f32_e32 v187, 0x3d372713, v39
	v_mul_f32_e32 v180, v102, v180
	v_mul_f32_e32 v181, v103, v181
	v_mul_f32_e32 v182, v104, v182
	v_mul_f32_e32 v183, v105, v183
	v_mul_f32_e32 v184, v36, v184
	v_mul_f32_e32 v185, v37, v185
	v_mul_f32_e32 v186, v38, v186
	v_mul_f32_e32 v187, v39, v187
	v_fma_f32 v180, v102, v180, v102
	v_fma_f32 v181, v103, v181, v103
	v_fma_f32 v182, v104, v182, v104
	v_fma_f32 v183, v105, v183, v105
	v_fma_f32 v184, v36, v184, v36
	v_fma_f32 v185, v37, v185, v37
	v_fma_f32 v186, v38, v186, v38
	v_fma_f32 v187, v39, v187, v39
	v_mul_f32_e32 v180, 0x3f4c422a, v180
	v_mul_f32_e32 v181, 0x3f4c422a, v181
	v_mul_f32_e32 v182, 0x3f4c422a, v182
	v_mul_f32_e32 v183, 0x3f4c422a, v183
	v_mul_f32_e32 v184, 0x3f4c422a, v184
	v_mul_f32_e32 v185, 0x3f4c422a, v185
	v_mul_f32_e32 v186, 0x3f4c422a, v186
	v_mul_f32_e32 v187, 0x3f4c422a, v187
	v_mul_f32_e32 v180, 0xc038aa3b, v180
	v_mul_f32_e32 v181, 0xc038aa3b, v181
	v_mul_f32_e32 v182, 0xc038aa3b, v182
	v_mul_f32_e32 v183, 0xc038aa3b, v183
	v_mul_f32_e32 v184, 0xc038aa3b, v184
	v_mul_f32_e32 v185, 0xc038aa3b, v185
	v_mul_f32_e32 v186, 0xc038aa3b, v186
	v_mul_f32_e32 v187, 0xc038aa3b, v187
	v_exp_f32_e32 v180, v180
	v_exp_f32_e32 v181, v181
	v_exp_f32_e32 v182, v182
	v_exp_f32_e32 v183, v183
	v_exp_f32_e32 v184, v184
	v_exp_f32_e32 v185, v185
	v_exp_f32_e32 v186, v186
	v_exp_f32_e32 v187, v187
	v_add_f32_e32 v180, 1.0, v180
	v_add_f32_e32 v181, 1.0, v181
	v_add_f32_e32 v182, 1.0, v182
	v_add_f32_e32 v183, 1.0, v183
	v_add_f32_e32 v184, 1.0, v184
	v_add_f32_e32 v185, 1.0, v185
	v_add_f32_e32 v186, 1.0, v186
	v_add_f32_e32 v187, 1.0, v187
	v_rcp_f32_e32 v180, v180
	v_rcp_f32_e32 v181, v181
	v_rcp_f32_e32 v182, v182
	v_rcp_f32_e32 v183, v183
	v_rcp_f32_e32 v184, v184
	v_rcp_f32_e32 v185, v185
	v_rcp_f32_e32 v186, v186
	v_rcp_f32_e32 v187, v187
	v_mul_f32_e32 v180, v102, v180
	v_mul_f32_e32 v181, v103, v181
	v_mul_f32_e32 v182, v104, v182
	v_mul_f32_e32 v183, v105, v183
	v_mul_f32_e32 v184, v36, v184
	v_mul_f32_e32 v185, v37, v185
	v_mul_f32_e32 v186, v38, v186
	v_mul_f32_e32 v187, v39, v187
	v_cvt_pk_bf16_f32 v136, v180, v181
	v_cvt_pk_bf16_f32 v137, v182, v183
	v_cvt_pk_bf16_f32 v138, v184, v185
	v_cvt_pk_bf16_f32 v139, v186, v187
	global_store_dwordx4 v140, v[136:139], s[0:1] offset:256
	s_add_u32 s0, s30, s7
	s_addc_u32 s1, s31, 0
; DI unsigned pk2(float lo, float hi) { f32x2 v = {lo, hi}; bf16x2_t b = __builtin_convertvector(v, bf16x2_t); return __builtin_bit_cast(unsigned, b); }
; DI float fexp2(float x) { return __builtin_amdgcn_exp2f(x); }
; DI float frcp(float x) { return __builtin_amdgcn_rcpf(x); }
;     __device__ __forceinline__ void operator()(const f32x4 (&acc)[2][2][4][2], const Unit& u, int wr, int wc, int fr, int fq) const {
;     ...
;                     if (mode == 1) {
; #pragma unroll
;                         for (int e = 0; e < 4; ++e) {
;                             { const float x = v0[e]; const float t = 0.7978845608028654f * (x + 0.044715f * x * x * x); v0[e] = x * frcp(1.f + fexp2(-2.f * LOG2E * t)); }
;                             { const float x = v1[e]; const float t = 0.7978845608028654f * (x + 0.044715f * x * x * x); v1[e] = x * frcp(1.f + fexp2(-2.f * LOG2E * t)); }
;                         }
;     ...
;                     u32x4 w; w.x = pk2(v0[0], v0[1]); w.y = pk2(v0[2], v0[3]); w.z = pk2(v1[0], v1[1]); w.w = pk2(v1[2], v1[3]);
;                     *(u32x4*)(C + (size_t)row * ldc + col0) = w;
	v_mul_f32_e32 v172, 0x3d372713, v88
	v_mul_f32_e32 v173, 0x3d372713, v89
	v_mul_f32_e32 v174, 0x3d372713, v90
	v_mul_f32_e32 v175, 0x3d372713, v91
	v_mul_f32_e32 v176, 0x3d372713, v24
	v_mul_f32_e32 v177, 0x3d372713, v25
	v_mul_f32_e32 v178, 0x3d372713, v26
	v_mul_f32_e32 v179, 0x3d372713, v27
	v_mul_f32_e32 v172, v88, v172
	v_mul_f32_e32 v173, v89, v173
	v_mul_f32_e32 v174, v90, v174
	v_mul_f32_e32 v175, v91, v175
	v_mul_f32_e32 v176, v24, v176
	v_mul_f32_e32 v177, v25, v177
	v_mul_f32_e32 v178, v26, v178
	v_mul_f32_e32 v179, v27, v179
	v_fma_f32 v172, v88, v172, v88
	v_fma_f32 v173, v89, v173, v89
	v_fma_f32 v174, v90, v174, v90
	v_fma_f32 v175, v91, v175, v91
	v_fma_f32 v176, v24, v176, v24
	v_fma_f32 v177, v25, v177, v25
	v_fma_f32 v178, v26, v178, v26
	v_fma_f32 v179, v27, v179, v27
	v_mul_f32_e32 v172, 0x3f4c422a, v172
	v_mul_f32_e32 v173, 0x3f4c422a, v173
	v_mul_f32_e32 v174, 0x3f4c422a, v174
	v_mul_f32_e32 v175, 0x3f4c422a, v175
	v_mul_f32_e32 v176, 0x3f4c422a, v176
	v_mul_f32_e32 v177, 0x3f4c422a, v177
	v_mul_f32_e32 v178, 0x3f4c422a, v178
	v_mul_f32_e32 v179, 0x3f4c422a, v179
	v_mul_f32_e32 v172, 0xc038aa3b, v172
	v_mul_f32_e32 v173, 0xc038aa3b, v173
	v_mul_f32_e32 v174, 0xc038aa3b, v174
	v_mul_f32_e32 v175, 0xc038aa3b, v175
	v_mul_f32_e32 v176, 0xc038aa3b, v176
	v_mul_f32_e32 v177, 0xc038aa3b, v177
	v_mul_f32_e32 v178, 0xc038aa3b, v178
	v_mul_f32_e32 v179, 0xc038aa3b, v179
	v_exp_f32_e32 v172, v172
	v_exp_f32_e32 v173, v173
	v_exp_f32_e32 v174, v174
	v_exp_f32_e32 v175, v175
	v_exp_f32_e32 v176, v176
	v_exp_f32_e32 v177, v177
	v_exp_f32_e32 v178, v178
	v_exp_f32_e32 v179, v179
	v_add_f32_e32 v172, 1.0, v172
	v_add_f32_e32 v173, 1.0, v173
	v_add_f32_e32 v174, 1.0, v174
	v_add_f32_e32 v175, 1.0, v175
	v_add_f32_e32 v176, 1.0, v176
	v_add_f32_e32 v177, 1.0, v177
	v_add_f32_e32 v178, 1.0, v178
	v_add_f32_e32 v179, 1.0, v179
	v_rcp_f32_e32 v172, v172
	v_rcp_f32_e32 v173, v173
	v_rcp_f32_e32 v174, v174
	v_rcp_f32_e32 v175, v175
	v_rcp_f32_e32 v176, v176
	v_rcp_f32_e32 v177, v177
	v_rcp_f32_e32 v178, v178
	v_rcp_f32_e32 v179, v179
	v_mul_f32_e32 v172, v88, v172
	v_mul_f32_e32 v173, v89, v173
	v_mul_f32_e32 v174, v90, v174
	v_mul_f32_e32 v175, v91, v175
	v_mul_f32_e32 v176, v24, v176
	v_mul_f32_e32 v177, v25, v177
	v_mul_f32_e32 v178, v26, v178
	v_mul_f32_e32 v179, v27, v179
	v_cvt_pk_bf16_f32 v132, v172, v173
	v_cvt_pk_bf16_f32 v133, v174, v175
	v_cvt_pk_bf16_f32 v134, v176, v177
	v_cvt_pk_bf16_f32 v135, v178, v179
	global_store_dwordx4 v140, v[132:135], s[0:1]
	v_mul_f32_e32 v180, 0x3d372713, v92
	v_mul_f32_e32 v181, 0x3d372713, v93
	v_mul_f32_e32 v182, 0x3d372713, v94
	v_mul_f32_e32 v183, 0x3d372713, v95
	v_mul_f32_e32 v184, 0x3d372713, v28
	v_mul_f32_e32 v185, 0x3d372713, v29
	v_mul_f32_e32 v186, 0x3d372713, v30
	v_mul_f32_e32 v187, 0x3d372713, v31
	v_mul_f32_e32 v180, v92, v180
	v_mul_f32_e32 v181, v93, v181
	v_mul_f32_e32 v182, v94, v182
	v_mul_f32_e32 v183, v95, v183
	v_mul_f32_e32 v184, v28, v184
	v_mul_f32_e32 v185, v29, v185
	v_mul_f32_e32 v186, v30, v186
	v_mul_f32_e32 v187, v31, v187
	v_fma_f32 v180, v92, v180, v92
	v_fma_f32 v181, v93, v181, v93
	v_fma_f32 v182, v94, v182, v94
	v_fma_f32 v183, v95, v183, v95
	v_fma_f32 v184, v28, v184, v28
	v_fma_f32 v185, v29, v185, v29
	v_fma_f32 v186, v30, v186, v30
	v_fma_f32 v187, v31, v187, v31
	v_mul_f32_e32 v180, 0x3f4c422a, v180
	v_mul_f32_e32 v181, 0x3f4c422a, v181
	v_mul_f32_e32 v182, 0x3f4c422a, v182
	v_mul_f32_e32 v183, 0x3f4c422a, v183
	v_mul_f32_e32 v184, 0x3f4c422a, v184
	v_mul_f32_e32 v185, 0x3f4c422a, v185
	v_mul_f32_e32 v186, 0x3f4c422a, v186
	v_mul_f32_e32 v187, 0x3f4c422a, v187
	v_mul_f32_e32 v180, 0xc038aa3b, v180
	v_mul_f32_e32 v181, 0xc038aa3b, v181
	v_mul_f32_e32 v182, 0xc038aa3b, v182
	v_mul_f32_e32 v183, 0xc038aa3b, v183
	v_mul_f32_e32 v184, 0xc038aa3b, v184
	v_mul_f32_e32 v185, 0xc038aa3b, v185
	v_mul_f32_e32 v186, 0xc038aa3b, v186
	v_mul_f32_e32 v187, 0xc038aa3b, v187
	v_exp_f32_e32 v180, v180
	v_exp_f32_e32 v181, v181
	v_exp_f32_e32 v182, v182
	v_exp_f32_e32 v183, v183
	v_exp_f32_e32 v184, v184
	v_exp_f32_e32 v185, v185
	v_exp_f32_e32 v186, v186
	v_exp_f32_e32 v187, v187
	v_add_f32_e32 v180, 1.0, v180
	v_add_f32_e32 v181, 1.0, v181
	v_add_f32_e32 v182, 1.0, v182
	v_add_f32_e32 v183, 1.0, v183
	v_add_f32_e32 v184, 1.0, v184
	v_add_f32_e32 v185, 1.0, v185
	v_add_f32_e32 v186, 1.0, v186
	v_add_f32_e32 v187, 1.0, v187
	v_rcp_f32_e32 v180, v180
	v_rcp_f32_e32 v181, v181
	v_rcp_f32_e32 v182, v182
	v_rcp_f32_e32 v183, v183
	v_rcp_f32_e32 v184, v184
	v_rcp_f32_e32 v185, v185
	v_rcp_f32_e32 v186, v186
	v_rcp_f32_e32 v187, v187
	v_mul_f32_e32 v180, v92, v180
	v_mul_f32_e32 v181, v93, v181
	v_mul_f32_e32 v182, v94, v182
	v_mul_f32_e32 v183, v95, v183
	v_mul_f32_e32 v184, v28, v184
	v_mul_f32_e32 v185, v29, v185
	v_mul_f32_e32 v186, v30, v186
	v_mul_f32_e32 v187, v31, v187
	v_cvt_pk_bf16_f32 v136, v180, v181
	v_cvt_pk_bf16_f32 v137, v182, v183
	v_cvt_pk_bf16_f32 v138, v184, v185
	v_cvt_pk_bf16_f32 v139, v186, v187
	global_store_dwordx4 v140, v[136:139], s[0:1] offset:256
	s_add_u32 s0, s0, s6
	s_addc_u32 s1, s1, 0
	v_mul_f32_e32 v172, 0x3d372713, v84
	v_mul_f32_e32 v173, 0x3d372713, v85
	v_mul_f32_e32 v174, 0x3d372713, v86
	v_mul_f32_e32 v175, 0x3d372713, v87
	v_mul_f32_e32 v176, 0x3d372713, v20
	v_mul_f32_e32 v177, 0x3d372713, v21
	v_mul_f32_e32 v178, 0x3d372713, v22
	v_mul_f32_e32 v179, 0x3d372713, v23
	v_mul_f32_e32 v172, v84, v172
	v_mul_f32_e32 v173, v85, v173
	v_mul_f32_e32 v174, v86, v174
	v_mul_f32_e32 v175, v87, v175
	v_mul_f32_e32 v176, v20, v176
	v_mul_f32_e32 v177, v21, v177
	v_mul_f32_e32 v178, v22, v178
	v_mul_f32_e32 v179, v23, v179
	v_fma_f32 v172, v84, v172, v84
; DI unsigned pk2(float lo, float hi) { f32x2 v = {lo, hi}; bf16x2_t b = __builtin_convertvector(v, bf16x2_t); return __builtin_bit_cast(unsigned, b); }
; DI float fexp2(float x) { return __builtin_amdgcn_exp2f(x); }
; DI float frcp(float x) { return __builtin_amdgcn_rcpf(x); }
;     __device__ __forceinline__ void operator()(const f32x4 (&acc)[2][2][4][2], const Unit& u, int wr, int wc, int fr, int fq) const {
;     ...
;                     if (mode == 1) {
; #pragma unroll
;                         for (int e = 0; e < 4; ++e) {
;                             { const float x = v0[e]; const float t = 0.7978845608028654f * (x + 0.044715f * x * x * x); v0[e] = x * frcp(1.f + fexp2(-2.f * LOG2E * t)); }
;                             { const float x = v1[e]; const float t = 0.7978845608028654f * (x + 0.044715f * x * x * x); v1[e] = x * frcp(1.f + fexp2(-2.f * LOG2E * t)); }
;                         }
;     ...
;                     u32x4 w; w.x = pk2(v0[0], v0[1]); w.y = pk2(v0[2], v0[3]); w.z = pk2(v1[0], v1[1]); w.w = pk2(v1[2], v1[3]);
;                     *(u32x4*)(C + (size_t)row * ldc + col0) = w;
	v_fma_f32 v173, v85, v173, v85
	v_fma_f32 v174, v86, v174, v86
	v_fma_f32 v175, v87, v175, v87
	v_fma_f32 v176, v20, v176, v20
	v_fma_f32 v177, v21, v177, v21
	v_fma_f32 v178, v22, v178, v22
	v_fma_f32 v179, v23, v179, v23
	v_mul_f32_e32 v172, 0x3f4c422a, v172
	v_mul_f32_e32 v173, 0x3f4c422a, v173
	v_mul_f32_e32 v174, 0x3f4c422a, v174
	v_mul_f32_e32 v175, 0x3f4c422a, v175
	v_mul_f32_e32 v176, 0x3f4c422a, v176
	v_mul_f32_e32 v177, 0x3f4c422a, v177
	v_mul_f32_e32 v178, 0x3f4c422a, v178
	v_mul_f32_e32 v179, 0x3f4c422a, v179
	v_mul_f32_e32 v172, 0xc038aa3b, v172
	v_mul_f32_e32 v173, 0xc038aa3b, v173
	v_mul_f32_e32 v174, 0xc038aa3b, v174
	v_mul_f32_e32 v175, 0xc038aa3b, v175
	v_mul_f32_e32 v176, 0xc038aa3b, v176
	v_mul_f32_e32 v177, 0xc038aa3b, v177
	v_mul_f32_e32 v178, 0xc038aa3b, v178
	v_mul_f32_e32 v179, 0xc038aa3b, v179
	v_exp_f32_e32 v172, v172
	v_exp_f32_e32 v173, v173
	v_exp_f32_e32 v174, v174
	v_exp_f32_e32 v175, v175
	v_exp_f32_e32 v176, v176
	v_exp_f32_e32 v177, v177
	v_exp_f32_e32 v178, v178
	v_exp_f32_e32 v179, v179
	v_add_f32_e32 v172, 1.0, v172
	v_add_f32_e32 v173, 1.0, v173
	v_add_f32_e32 v174, 1.0, v174
	v_add_f32_e32 v175, 1.0, v175
	v_add_f32_e32 v176, 1.0, v176
	v_add_f32_e32 v177, 1.0, v177
	v_add_f32_e32 v178, 1.0, v178
	v_add_f32_e32 v179, 1.0, v179
	v_rcp_f32_e32 v172, v172
	v_rcp_f32_e32 v173, v173
	v_rcp_f32_e32 v174, v174
	v_rcp_f32_e32 v175, v175
	v_rcp_f32_e32 v176, v176
	v_rcp_f32_e32 v177, v177
	v_rcp_f32_e32 v178, v178
	v_rcp_f32_e32 v179, v179
	v_mul_f32_e32 v172, v84, v172
	v_mul_f32_e32 v173, v85, v173
	v_mul_f32_e32 v174, v86, v174
	v_mul_f32_e32 v175, v87, v175
	v_mul_f32_e32 v176, v20, v176
	v_mul_f32_e32 v177, v21, v177
	v_mul_f32_e32 v178, v22, v178
	v_mul_f32_e32 v179, v23, v179
	v_cvt_pk_bf16_f32 v132, v172, v173
	v_cvt_pk_bf16_f32 v133, v174, v175
	v_cvt_pk_bf16_f32 v134, v176, v177
	v_cvt_pk_bf16_f32 v135, v178, v179
	global_store_dwordx4 v140, v[132:135], s[0:1]
	v_mul_f32_e32 v180, 0x3d372713, v80
	v_mul_f32_e32 v181, 0x3d372713, v81
	v_mul_f32_e32 v182, 0x3d372713, v82
	v_mul_f32_e32 v183, 0x3d372713, v83
	v_mul_f32_e32 v184, 0x3d372713, v16
	v_mul_f32_e32 v185, 0x3d372713, v17
	v_mul_f32_e32 v186, 0x3d372713, v18
	v_mul_f32_e32 v187, 0x3d372713, v19
	v_mul_f32_e32 v180, v80, v180
	v_mul_f32_e32 v181, v81, v181
	v_mul_f32_e32 v182, v82, v182
	v_mul_f32_e32 v183, v83, v183
	v_mul_f32_e32 v184, v16, v184
	v_mul_f32_e32 v185, v17, v185
	v_mul_f32_e32 v186, v18, v186
	v_mul_f32_e32 v187, v19, v187
	v_fma_f32 v180, v80, v180, v80
	v_fma_f32 v181, v81, v181, v81
	v_fma_f32 v182, v82, v182, v82
	v_fma_f32 v183, v83, v183, v83
	v_fma_f32 v184, v16, v184, v16
	v_fma_f32 v185, v17, v185, v17
	v_fma_f32 v186, v18, v186, v18
	v_fma_f32 v187, v19, v187, v19
	v_mul_f32_e32 v180, 0x3f4c422a, v180
	v_mul_f32_e32 v181, 0x3f4c422a, v181
	v_mul_f32_e32 v182, 0x3f4c422a, v182
	v_mul_f32_e32 v183, 0x3f4c422a, v183
	v_mul_f32_e32 v184, 0x3f4c422a, v184
	v_mul_f32_e32 v185, 0x3f4c422a, v185
	v_mul_f32_e32 v186, 0x3f4c422a, v186
	v_mul_f32_e32 v187, 0x3f4c422a, v187
	v_mul_f32_e32 v180, 0xc038aa3b, v180
	v_mul_f32_e32 v181, 0xc038aa3b, v181
	v_mul_f32_e32 v182, 0xc038aa3b, v182
	v_mul_f32_e32 v183, 0xc038aa3b, v183
	v_mul_f32_e32 v184, 0xc038aa3b, v184
	v_mul_f32_e32 v185, 0xc038aa3b, v185
	v_mul_f32_e32 v186, 0xc038aa3b, v186
	v_mul_f32_e32 v187, 0xc038aa3b, v187
	v_exp_f32_e32 v180, v180
	v_exp_f32_e32 v181, v181
	v_exp_f32_e32 v182, v182
	v_exp_f32_e32 v183, v183
	v_exp_f32_e32 v184, v184
	v_exp_f32_e32 v185, v185
	v_exp_f32_e32 v186, v186
	v_exp_f32_e32 v187, v187
	v_add_f32_e32 v180, 1.0, v180
	v_add_f32_e32 v181, 1.0, v181
	v_add_f32_e32 v182, 1.0, v182
	v_add_f32_e32 v183, 1.0, v183
	v_add_f32_e32 v184, 1.0, v184
	v_add_f32_e32 v185, 1.0, v185
	v_add_f32_e32 v186, 1.0, v186
	v_add_f32_e32 v187, 1.0, v187
	v_rcp_f32_e32 v180, v180
	v_rcp_f32_e32 v181, v181
	v_rcp_f32_e32 v182, v182
	v_rcp_f32_e32 v183, v183
	v_rcp_f32_e32 v184, v184
	v_rcp_f32_e32 v185, v185
	v_rcp_f32_e32 v186, v186
	v_rcp_f32_e32 v187, v187
	v_mul_f32_e32 v180, v80, v180
	v_mul_f32_e32 v181, v81, v181
	v_mul_f32_e32 v182, v82, v182
	v_mul_f32_e32 v183, v83, v183
	v_mul_f32_e32 v184, v16, v184
	v_mul_f32_e32 v185, v17, v185
	v_mul_f32_e32 v186, v18, v186
	v_mul_f32_e32 v187, v19, v187
	v_cvt_pk_bf16_f32 v136, v180, v181
	v_cvt_pk_bf16_f32 v137, v182, v183
	v_cvt_pk_bf16_f32 v138, v184, v185
	v_cvt_pk_bf16_f32 v139, v186, v187
	global_store_dwordx4 v140, v[136:139], s[0:1] offset:256
	s_add_u32 s0, s0, s6
	s_addc_u32 s1, s1, 0
	v_mul_f32_e32 v172, 0x3d372713, v76
	v_mul_f32_e32 v173, 0x3d372713, v77
	v_mul_f32_e32 v174, 0x3d372713, v78
	v_mul_f32_e32 v175, 0x3d372713, v79
	v_mul_f32_e32 v176, 0x3d372713, v12
	v_mul_f32_e32 v177, 0x3d372713, v13
	v_mul_f32_e32 v178, 0x3d372713, v14
	v_mul_f32_e32 v179, 0x3d372713, v15
	v_mul_f32_e32 v172, v76, v172
	v_mul_f32_e32 v173, v77, v173
	v_mul_f32_e32 v174, v78, v174
	v_mul_f32_e32 v175, v79, v175
	v_mul_f32_e32 v176, v12, v176
	v_mul_f32_e32 v177, v13, v177
	v_mul_f32_e32 v178, v14, v178
	v_mul_f32_e32 v179, v15, v179
	v_fma_f32 v172, v76, v172, v76
	v_fma_f32 v173, v77, v173, v77
	v_fma_f32 v174, v78, v174, v78
	v_fma_f32 v175, v79, v175, v79
	v_fma_f32 v176, v12, v176, v12
	v_fma_f32 v177, v13, v177, v13
	v_fma_f32 v178, v14, v178, v14
	v_fma_f32 v179, v15, v179, v15
	v_mul_f32_e32 v172, 0x3f4c422a, v172
	v_mul_f32_e32 v173, 0x3f4c422a, v173
	v_mul_f32_e32 v174, 0x3f4c422a, v174
	v_mul_f32_e32 v175, 0x3f4c422a, v175
	v_mul_f32_e32 v176, 0x3f4c422a, v176
	v_mul_f32_e32 v177, 0x3f4c422a, v177
	v_mul_f32_e32 v178, 0x3f4c422a, v178
	v_mul_f32_e32 v179, 0x3f4c422a, v179
	v_mul_f32_e32 v172, 0xc038aa3b, v172
; DI unsigned pk2(float lo, float hi) { f32x2 v = {lo, hi}; bf16x2_t b = __builtin_convertvector(v, bf16x2_t); return __builtin_bit_cast(unsigned, b); }
; DI float fexp2(float x) { return __builtin_amdgcn_exp2f(x); }
; DI float frcp(float x) { return __builtin_amdgcn_rcpf(x); }
;     __device__ __forceinline__ void operator()(const f32x4 (&acc)[2][2][4][2], const Unit& u, int wr, int wc, int fr, int fq) const {
;     ...
;                     if (mode == 1) {
; #pragma unroll
;                         for (int e = 0; e < 4; ++e) {
;                             { const float x = v0[e]; const float t = 0.7978845608028654f * (x + 0.044715f * x * x * x); v0[e] = x * frcp(1.f + fexp2(-2.f * LOG2E * t)); }
;                             { const float x = v1[e]; const float t = 0.7978845608028654f * (x + 0.044715f * x * x * x); v1[e] = x * frcp(1.f + fexp2(-2.f * LOG2E * t)); }
;                         }
;     ...
;                     u32x4 w; w.x = pk2(v0[0], v0[1]); w.y = pk2(v0[2], v0[3]); w.z = pk2(v1[0], v1[1]); w.w = pk2(v1[2], v1[3]);
;                     *(u32x4*)(C + (size_t)row * ldc + col0) = w;
	v_mul_f32_e32 v173, 0xc038aa3b, v173
	v_mul_f32_e32 v174, 0xc038aa3b, v174
	v_mul_f32_e32 v175, 0xc038aa3b, v175
	v_mul_f32_e32 v176, 0xc038aa3b, v176
	v_mul_f32_e32 v177, 0xc038aa3b, v177
	v_mul_f32_e32 v178, 0xc038aa3b, v178
	v_mul_f32_e32 v179, 0xc038aa3b, v179
	v_exp_f32_e32 v172, v172
	v_exp_f32_e32 v173, v173
	v_exp_f32_e32 v174, v174
	v_exp_f32_e32 v175, v175
	v_exp_f32_e32 v176, v176
	v_exp_f32_e32 v177, v177
	v_exp_f32_e32 v178, v178
	v_exp_f32_e32 v179, v179
	v_add_f32_e32 v172, 1.0, v172
	v_add_f32_e32 v173, 1.0, v173
	v_add_f32_e32 v174, 1.0, v174
	v_add_f32_e32 v175, 1.0, v175
	v_add_f32_e32 v176, 1.0, v176
	v_add_f32_e32 v177, 1.0, v177
	v_add_f32_e32 v178, 1.0, v178
	v_add_f32_e32 v179, 1.0, v179
	v_rcp_f32_e32 v172, v172
	v_rcp_f32_e32 v173, v173
	v_rcp_f32_e32 v174, v174
	v_rcp_f32_e32 v175, v175
	v_rcp_f32_e32 v176, v176
	v_rcp_f32_e32 v177, v177
	v_rcp_f32_e32 v178, v178
	v_rcp_f32_e32 v179, v179
	v_mul_f32_e32 v172, v76, v172
	v_mul_f32_e32 v173, v77, v173
	v_mul_f32_e32 v174, v78, v174
	v_mul_f32_e32 v175, v79, v175
	v_mul_f32_e32 v176, v12, v176
	v_mul_f32_e32 v177, v13, v177
	v_mul_f32_e32 v178, v14, v178
	v_mul_f32_e32 v179, v15, v179
	v_cvt_pk_bf16_f32 v132, v172, v173
	v_cvt_pk_bf16_f32 v133, v174, v175
	v_cvt_pk_bf16_f32 v134, v176, v177
	v_cvt_pk_bf16_f32 v135, v178, v179
	global_store_dwordx4 v140, v[132:135], s[0:1]
	v_mul_f32_e32 v180, 0x3d372713, v72
	v_mul_f32_e32 v181, 0x3d372713, v73
	v_mul_f32_e32 v182, 0x3d372713, v74
	v_mul_f32_e32 v183, 0x3d372713, v75
	v_mul_f32_e32 v184, 0x3d372713, v8
	v_mul_f32_e32 v185, 0x3d372713, v9
	v_mul_f32_e32 v186, 0x3d372713, v10
	v_mul_f32_e32 v187, 0x3d372713, v11
	v_mul_f32_e32 v180, v72, v180
	v_mul_f32_e32 v181, v73, v181
	v_mul_f32_e32 v182, v74, v182
	v_mul_f32_e32 v183, v75, v183
	v_mul_f32_e32 v184, v8, v184
	v_mul_f32_e32 v185, v9, v185
	v_mul_f32_e32 v186, v10, v186
	v_mul_f32_e32 v187, v11, v187
	v_fma_f32 v180, v72, v180, v72
	v_fma_f32 v181, v73, v181, v73
	v_fma_f32 v182, v74, v182, v74
	v_fma_f32 v183, v75, v183, v75
	v_fma_f32 v184, v8, v184, v8
	v_fma_f32 v185, v9, v185, v9
	v_fma_f32 v186, v10, v186, v10
	v_fma_f32 v187, v11, v187, v11
	v_mul_f32_e32 v180, 0x3f4c422a, v180
	v_mul_f32_e32 v181, 0x3f4c422a, v181
	v_mul_f32_e32 v182, 0x3f4c422a, v182
	v_mul_f32_e32 v183, 0x3f4c422a, v183
	v_mul_f32_e32 v184, 0x3f4c422a, v184
	v_mul_f32_e32 v185, 0x3f4c422a, v185
	v_mul_f32_e32 v186, 0x3f4c422a, v186
	v_mul_f32_e32 v187, 0x3f4c422a, v187
	v_mul_f32_e32 v180, 0xc038aa3b, v180
	v_mul_f32_e32 v181, 0xc038aa3b, v181
	v_mul_f32_e32 v182, 0xc038aa3b, v182
	v_mul_f32_e32 v183, 0xc038aa3b, v183
	v_mul_f32_e32 v184, 0xc038aa3b, v184
	v_mul_f32_e32 v185, 0xc038aa3b, v185
	v_mul_f32_e32 v186, 0xc038aa3b, v186
	v_mul_f32_e32 v187, 0xc038aa3b, v187
	v_exp_f32_e32 v180, v180
	v_exp_f32_e32 v181, v181
	v_exp_f32_e32 v182, v182
	v_exp_f32_e32 v183, v183
	v_exp_f32_e32 v184, v184
	v_exp_f32_e32 v185, v185
	v_exp_f32_e32 v186, v186
	v_exp_f32_e32 v187, v187
	v_add_f32_e32 v180, 1.0, v180
	v_add_f32_e32 v181, 1.0, v181
	v_add_f32_e32 v182, 1.0, v182
	v_add_f32_e32 v183, 1.0, v183
	v_add_f32_e32 v184, 1.0, v184
	v_add_f32_e32 v185, 1.0, v185
	v_add_f32_e32 v186, 1.0, v186
	v_add_f32_e32 v187, 1.0, v187
	v_rcp_f32_e32 v180, v180
	v_rcp_f32_e32 v181, v181
	v_rcp_f32_e32 v182, v182
	v_rcp_f32_e32 v183, v183
	v_rcp_f32_e32 v184, v184
	v_rcp_f32_e32 v185, v185
	v_rcp_f32_e32 v186, v186
	v_rcp_f32_e32 v187, v187
	v_mul_f32_e32 v180, v72, v180
	v_mul_f32_e32 v181, v73, v181
	v_mul_f32_e32 v182, v74, v182
	v_mul_f32_e32 v183, v75, v183
	v_mul_f32_e32 v184, v8, v184
	v_mul_f32_e32 v185, v9, v185
	v_mul_f32_e32 v186, v10, v186
	v_mul_f32_e32 v187, v11, v187
	v_cvt_pk_bf16_f32 v136, v180, v181
	v_cvt_pk_bf16_f32 v137, v182, v183
	v_cvt_pk_bf16_f32 v138, v184, v185
	v_cvt_pk_bf16_f32 v139, v186, v187
	global_store_dwordx4 v140, v[136:139], s[0:1] offset:256
	s_add_u32 s0, s0, s6
	s_addc_u32 s1, s1, 0
	v_mul_f32_e32 v172, 0x3d372713, v64
	v_mul_f32_e32 v173, 0x3d372713, v65
	v_mul_f32_e32 v174, 0x3d372713, v66
	v_mul_f32_e32 v175, 0x3d372713, v67
	v_mul_f32_e32 v176, 0x3d372713, v0
	v_mul_f32_e32 v177, 0x3d372713, v1
	v_mul_f32_e32 v178, 0x3d372713, v2
	v_mul_f32_e32 v179, 0x3d372713, v3
	v_mul_f32_e32 v172, v64, v172
	v_mul_f32_e32 v173, v65, v173
	v_mul_f32_e32 v174, v66, v174
	v_mul_f32_e32 v175, v67, v175
	v_mul_f32_e32 v176, v0, v176
	v_mul_f32_e32 v177, v1, v177
	v_mul_f32_e32 v178, v2, v178
	v_mul_f32_e32 v179, v3, v179
; DI unsigned pk2(float lo, float hi) { f32x2 v = {lo, hi}; bf16x2_t b = __builtin_convertvector(v, bf16x2_t); return __builtin_bit_cast(unsigned, b); }
; DI float fexp2(float x) { return __builtin_amdgcn_exp2f(x); }
; DI float frcp(float x) { return __builtin_amdgcn_rcpf(x); }
;     __device__ __forceinline__ void operator()(const f32x4 (&acc)[2][2][4][2], const Unit& u, int wr, int wc, int fr, int fq) const {
;     ...
;                     if (mode == 1) {
; #pragma unroll
;                         for (int e = 0; e < 4; ++e) {
;                             { const float x = v0[e]; const float t = 0.7978845608028654f * (x + 0.044715f * x * x * x); v0[e] = x * frcp(1.f + fexp2(-2.f * LOG2E * t)); }
;                             { const float x = v1[e]; const float t = 0.7978845608028654f * (x + 0.044715f * x * x * x); v1[e] = x * frcp(1.f + fexp2(-2.f * LOG2E * t)); }
;                         }
;     ...
;                     u32x4 w; w.x = pk2(v0[0], v0[1]); w.y = pk2(v0[2], v0[3]); w.z = pk2(v1[0], v1[1]); w.w = pk2(v1[2], v1[3]);
;                     *(u32x4*)(C + (size_t)row * ldc + col0) = w;
	v_fma_f32 v172, v64, v172, v64
	v_fma_f32 v173, v65, v173, v65
	v_fma_f32 v174, v66, v174, v66
	v_fma_f32 v175, v67, v175, v67
	v_fma_f32 v176, v0, v176, v0
	v_fma_f32 v177, v1, v177, v1
	v_fma_f32 v178, v2, v178, v2
	v_fma_f32 v179, v3, v179, v3
	v_mul_f32_e32 v172, 0x3f4c422a, v172
	v_mul_f32_e32 v173, 0x3f4c422a, v173
	v_mul_f32_e32 v174, 0x3f4c422a, v174
	v_mul_f32_e32 v175, 0x3f4c422a, v175
	v_mul_f32_e32 v176, 0x3f4c422a, v176
	v_mul_f32_e32 v177, 0x3f4c422a, v177
	v_mul_f32_e32 v178, 0x3f4c422a, v178
	v_mul_f32_e32 v179, 0x3f4c422a, v179
	v_mul_f32_e32 v172, 0xc038aa3b, v172
	v_mul_f32_e32 v173, 0xc038aa3b, v173
	v_mul_f32_e32 v174, 0xc038aa3b, v174
	v_mul_f32_e32 v175, 0xc038aa3b, v175
	v_mul_f32_e32 v176, 0xc038aa3b, v176
	v_mul_f32_e32 v177, 0xc038aa3b, v177
	v_mul_f32_e32 v178, 0xc038aa3b, v178
	v_mul_f32_e32 v179, 0xc038aa3b, v179
	v_exp_f32_e32 v172, v172
	v_exp_f32_e32 v173, v173
	v_exp_f32_e32 v174, v174
	v_exp_f32_e32 v175, v175
	v_exp_f32_e32 v176, v176
	v_exp_f32_e32 v177, v177
	v_exp_f32_e32 v178, v178
	v_exp_f32_e32 v179, v179
	v_add_f32_e32 v172, 1.0, v172
	v_add_f32_e32 v173, 1.0, v173
	v_add_f32_e32 v174, 1.0, v174
	v_add_f32_e32 v175, 1.0, v175
	v_add_f32_e32 v176, 1.0, v176
	v_add_f32_e32 v177, 1.0, v177
	v_add_f32_e32 v178, 1.0, v178
	v_add_f32_e32 v179, 1.0, v179
	v_rcp_f32_e32 v172, v172
	v_rcp_f32_e32 v173, v173
	v_rcp_f32_e32 v174, v174
	v_rcp_f32_e32 v175, v175
	v_rcp_f32_e32 v176, v176
	v_rcp_f32_e32 v177, v177
	v_rcp_f32_e32 v178, v178
	v_rcp_f32_e32 v179, v179
	v_mul_f32_e32 v172, v64, v172
	v_mul_f32_e32 v173, v65, v173
	v_mul_f32_e32 v174, v66, v174
	v_mul_f32_e32 v175, v67, v175
	v_mul_f32_e32 v176, v0, v176
	v_mul_f32_e32 v177, v1, v177
	v_mul_f32_e32 v178, v2, v178
	v_mul_f32_e32 v179, v3, v179
	v_cvt_pk_bf16_f32 v132, v172, v173
	v_cvt_pk_bf16_f32 v133, v174, v175
	v_cvt_pk_bf16_f32 v134, v176, v177
	v_cvt_pk_bf16_f32 v135, v178, v179
	global_store_dwordx4 v140, v[132:135], s[0:1]
	v_mul_f32_e32 v180, 0x3d372713, v68
	v_mul_f32_e32 v181, 0x3d372713, v69
	v_mul_f32_e32 v182, 0x3d372713, v70
	v_mul_f32_e32 v183, 0x3d372713, v71
	v_mul_f32_e32 v184, 0x3d372713, v4
	v_mul_f32_e32 v185, 0x3d372713, v5
	v_mul_f32_e32 v186, 0x3d372713, v6
	v_mul_f32_e32 v187, 0x3d372713, v7
	v_mul_f32_e32 v180, v68, v180
	v_mul_f32_e32 v181, v69, v181
	v_mul_f32_e32 v182, v70, v182
	v_mul_f32_e32 v183, v71, v183
	v_mul_f32_e32 v184, v4, v184
	v_mul_f32_e32 v185, v5, v185
	v_mul_f32_e32 v186, v6, v186
	v_mul_f32_e32 v187, v7, v187
	v_fma_f32 v180, v68, v180, v68
	v_fma_f32 v181, v69, v181, v69
	v_fma_f32 v182, v70, v182, v70
	v_fma_f32 v183, v71, v183, v71
	v_fma_f32 v184, v4, v184, v4
	v_fma_f32 v185, v5, v185, v5
	v_fma_f32 v186, v6, v186, v6
	v_fma_f32 v187, v7, v187, v7
	v_mul_f32_e32 v180, 0x3f4c422a, v180
	v_mul_f32_e32 v181, 0x3f4c422a, v181
	v_mul_f32_e32 v182, 0x3f4c422a, v182
	v_mul_f32_e32 v183, 0x3f4c422a, v183
	v_mul_f32_e32 v184, 0x3f4c422a, v184
	v_mul_f32_e32 v185, 0x3f4c422a, v185
	v_mul_f32_e32 v186, 0x3f4c422a, v186
	v_mul_f32_e32 v187, 0x3f4c422a, v187
	v_mul_f32_e32 v180, 0xc038aa3b, v180
	v_mul_f32_e32 v181, 0xc038aa3b, v181
	v_mul_f32_e32 v182, 0xc038aa3b, v182
	v_mul_f32_e32 v183, 0xc038aa3b, v183
	v_mul_f32_e32 v184, 0xc038aa3b, v184
	v_mul_f32_e32 v185, 0xc038aa3b, v185
	v_mul_f32_e32 v186, 0xc038aa3b, v186
	v_mul_f32_e32 v187, 0xc038aa3b, v187
	v_exp_f32_e32 v180, v180
	v_exp_f32_e32 v181, v181
	v_exp_f32_e32 v182, v182
	v_exp_f32_e32 v183, v183
	v_exp_f32_e32 v184, v184
	v_exp_f32_e32 v185, v185
	v_exp_f32_e32 v186, v186
	v_exp_f32_e32 v187, v187
	v_add_f32_e32 v180, 1.0, v180
	v_add_f32_e32 v181, 1.0, v181
	v_add_f32_e32 v182, 1.0, v182
	v_add_f32_e32 v183, 1.0, v183
	v_add_f32_e32 v184, 1.0, v184
	v_add_f32_e32 v185, 1.0, v185
	v_add_f32_e32 v186, 1.0, v186
	v_add_f32_e32 v187, 1.0, v187
	v_rcp_f32_e32 v180, v180
	v_rcp_f32_e32 v181, v181
	v_rcp_f32_e32 v182, v182
	v_rcp_f32_e32 v183, v183
	v_rcp_f32_e32 v184, v184
	v_rcp_f32_e32 v185, v185
	v_rcp_f32_e32 v186, v186
	v_rcp_f32_e32 v187, v187
	v_mul_f32_e32 v180, v68, v180
	v_mul_f32_e32 v181, v69, v181
	v_mul_f32_e32 v182, v70, v182
	v_mul_f32_e32 v183, v71, v183
	v_mul_f32_e32 v184, v4, v184
	v_mul_f32_e32 v185, v5, v185
	v_mul_f32_e32 v186, v6, v186
	v_mul_f32_e32 v187, v7, v187
	v_cvt_pk_bf16_f32 v136, v180, v181
	v_cvt_pk_bf16_f32 v137, v182, v183
	v_cvt_pk_bf16_f32 v138, v184, v185
	v_cvt_pk_bf16_f32 v139, v186, v187
	global_store_dwordx4 v140, v[136:139], s[0:1] offset:256
	s_branch .LBB0_954
